# nt hint also on the converted bf16 weight stores and on the first row phase's f32 x loads
# speedup vs baseline: 1.0059x; 1.0059x over previous
.LBB0_82:
	v_min_i32_e32 v0, 0x2000, v128
	v_cmp_gt_i32_e32 vcc, s33, v128
	v_ashrrev_i32_e32 v18, 11, v0
	v_mov_b32_e32 v0, s85
	v_mov_b32_e32 v1, s81
	v_cndmask_b32_e32 v1, v0, v1, vcc
	v_mov_b32_e32 v0, s84
	v_mov_b32_e32 v2, s80
	v_cndmask_b32_e32 v0, v0, v2, vcc
	v_add_u32_e32 v2, 0xffffe000, v128
	v_mov_b32_e32 v132, v134
	v_cndmask_b32_e32 v3, 0, v129, vcc
	v_cndmask_b32_e32 v2, v2, v128, vcc
	v_lshlrev_b64 v[2:3], 13, v[2:3]
	v_ashrrev_i32_e32 v133, 31, v132
	v_lshl_add_u64 v[0:1], v[0:1], 0, v[2:3]
	v_lshlrev_b64 v[16:17], 2, v[132:133]
	v_lshl_add_u64 v[0:1], v[0:1], 0, v[16:17]
	global_load_dwordx4 v[92:95], v[0:1], off nt
	global_load_dwordx4 v[68:71], v[0:1], off offset:1024 nt
	global_load_dwordx4 v[44:47], v[0:1], off offset:2048 nt
	global_load_dwordx4 v[28:31], v[0:1], off offset:3072 nt
	v_add_co_u32_e32 v0, vcc, s30, v0
	v_mul_hi_i32_i24_e32 v19, 0xc000, v18
	s_nop 0
	v_addc_co_u32_e32 v1, vcc, 0, v1, vcc
	global_load_dwordx4 v[12:15], v[0:1], off nt
	global_load_dwordx4 v[8:11], v[0:1], off offset:1024 nt
	global_load_dwordx4 v[4:7], v[0:1], off offset:2048 nt
	s_nop 0
	global_load_dwordx4 v[0:3], v[0:1], off offset:3072 nt
	v_mul_i32_i24_e32 v18, 0xc000, v18
	v_lshl_add_u64 v[18:19], s[52:53], 0, v[18:19]
	v_lshl_add_u64 v[18:19], v[18:19], 0, v[16:17]
	v_lshl_add_u64 v[16:17], s[92:93], 0, v[16:17]
	global_load_dwordx4 v[120:123], v[16:17], off
	global_load_dwordx4 v[116:119], v[18:19], off
	v_add_co_u32_e32 v24, vcc, s66, v18
	v_lshl_add_u64 v[20:21], v[18:19], 0, s[78:79]
	s_nop 0
	v_addc_co_u32_e32 v25, vcc, 0, v19, vcc
	global_load_dwordx4 v[124:127], v[24:25], off offset:-4096
	global_load_dwordx4 v[108:111], v[16:17], off offset:1024
	global_load_dwordx4 v[104:107], v[18:19], off offset:1024
	global_load_dwordx4 v[112:115], v[20:21], off offset:1024
	global_load_dwordx4 v[96:99], v[16:17], off offset:2048
	global_load_dwordx4 v[88:91], v[18:19], off offset:2048
	global_load_dwordx4 v[100:103], v[20:21], off offset:2048
	global_load_dwordx4 v[80:83], v[16:17], off offset:3072
	global_load_dwordx4 v[72:75], v[18:19], off offset:3072
	global_load_dwordx4 v[84:87], v[20:21], off offset:3072
	v_add_co_u32_e32 v16, vcc, s30, v16
	v_lshl_add_u64 v[128:129], v[128:129], 0, s[50:51]
	s_nop 0
	v_addc_co_u32_e32 v17, vcc, 0, v17, vcc
	global_load_dwordx4 v[64:67], v[16:17], off
	v_add_co_u32_e32 v18, vcc, s30, v18
	s_movk_i32 s2, 0x23ff
	s_nop 0
	v_addc_co_u32_e32 v19, vcc, 0, v19, vcc
	global_load_dwordx4 v[60:63], v[18:19], off
	global_load_dwordx4 v[76:79], v[24:25], off
	global_load_dwordx4 v[52:55], v[16:17], off offset:1024
	global_load_dwordx4 v[48:51], v[18:19], off offset:1024
	global_load_dwordx4 v[56:59], v[24:25], off offset:1024
	global_load_dwordx4 v[36:39], v[16:17], off offset:2048
	global_load_dwordx4 v[32:35], v[18:19], off offset:2048
	global_load_dwordx4 v[40:43], v[24:25], off offset:2048
	global_load_dwordx4 v[20:23], v[16:17], off offset:3072
	s_nop 0
	global_load_dwordx4 v[16:19], v[18:19], off offset:3072
	s_nop 0
	global_load_dwordx4 v[24:27], v[24:25], off offset:3072
	s_waitcnt vmcnt(0)
	v_mov_b32_e32 v138, v93
	v_mov_b32_e32 v139, v69
	v_mov_b32_e32 v136, v92
	v_mov_b32_e32 v137, v68
	v_pk_mul_f32 v[138:139], v[138:139], v[138:139]
	v_mov_b32_e32 v140, v95
	v_mov_b32_e32 v141, v71
	v_pk_fma_f32 v[136:137], v[136:137], v[136:137], v[138:139]
	v_mov_b32_e32 v138, v94
	v_mov_b32_e32 v139, v70
	v_pk_mul_f32 v[140:141], v[140:141], v[140:141]
	v_mul_f32_e32 v135, v12, v12
	v_pk_fma_f32 v[138:139], v[138:139], v[138:139], v[140:141]
	v_pk_mul_f32 v[140:141], v[44:45], v[44:45]
	v_pk_add_f32 v[136:137], v[136:137], v[138:139]
	v_pk_mul_f32 v[138:139], v[46:47], v[46:47]
	v_pk_add_f32 v[136:137], v[136:137], v[136:137] op_sel:[0,1] op_sel_hi:[1,0]
	v_pk_mov_b32 v[142:143], v[140:141], v[138:139] op_sel:[1,0]
	v_mov_b32_e32 v141, v139
	v_pk_add_f32 v[138:139], v[142:143], v[140:141]
	v_mul_f32_e32 v140, v13, v13
	v_pk_add_f32 v[138:139], v[138:139], v[138:139] op_sel:[0,1] op_sel_hi:[1,0]
	v_mov_b32_e32 v137, v135
	v_mov_b32_e32 v139, v140
	v_pk_add_f32 v[136:137], v[136:137], v[138:139]
	v_mul_f32_e32 v138, v29, v29
	v_mul_f32_e32 v141, v14, v14
	v_pk_fma_f32 v[138:139], v[28:29], v[28:29], v[138:139] op_sel_hi:[1,1,0]
	v_mul_f32_e32 v140, v31, v31
	v_mul_f32_e32 v142, v15, v15
	v_mov_b32_e32 v139, v141
	v_pk_fma_f32 v[140:141], v[30:31], v[30:31], v[140:141] op_sel_hi:[1,1,0]
	v_mul_f32_e32 v135, v0, v0
	v_mov_b32_e32 v141, v142
	v_pk_add_f32 v[138:139], v[138:139], v[140:141]
	v_pk_mul_f32 v[140:141], v[8:9], v[8:9]
	v_pk_add_f32 v[136:137], v[136:137], v[138:139]
	v_pk_mul_f32 v[138:139], v[10:11], v[10:11]
	v_pk_add_f32 v[136:137], v[136:137], v[136:137] op_sel:[0,1] op_sel_hi:[1,0]
	v_pk_mov_b32 v[142:143], v[140:141], v[138:139] op_sel:[1,0]
	v_mov_b32_e32 v141, v139
	v_pk_add_f32 v[138:139], v[142:143], v[140:141]
	v_mul_f32_e32 v140, v1, v1
	v_pk_add_f32 v[138:139], v[138:139], v[138:139] op_sel:[0,1] op_sel_hi:[1,0]
	v_mov_b32_e32 v137, v135
	v_mov_b32_e32 v139, v140
	v_pk_add_f32 v[136:137], v[136:137], v[138:139]
	v_mul_f32_e32 v138, v5, v5
	v_mul_f32_e32 v141, v2, v2
	v_pk_fma_f32 v[138:139], v[4:5], v[4:5], v[138:139] op_sel_hi:[1,1,0]
	v_mul_f32_e32 v140, v7, v7
	v_mul_f32_e32 v142, v3, v3
	v_mov_b32_e32 v139, v141
	v_pk_fma_f32 v[140:141], v[6:7], v[6:7], v[140:141] op_sel_hi:[1,1,0]
	s_nop 0
	v_mov_b32_e32 v141, v142
	v_pk_add_f32 v[138:139], v[138:139], v[140:141]
	s_nop 0
	v_pk_add_f32 v[136:137], v[136:137], v[138:139]
	s_nop 0
	v_add_f32_e32 v135, v136, v137
	v_and_b32_e32 v136, 64, v229
	v_add_u32_e32 v136, 64, v136
	v_xor_b32_e32 v137, 1, v229
	v_cmp_lt_i32_e32 vcc, v137, v136
	s_nop 1
	v_cndmask_b32_e32 v137, v229, v137, vcc
	v_lshlrev_b32_e32 v137, 2, v137
	ds_bpermute_b32 v137, v137, v135
	s_waitcnt lgkmcnt(0)
	v_add_f32_e32 v135, v135, v137
	v_xor_b32_e32 v137, 2, v229
	v_cmp_lt_i32_e32 vcc, v137, v136
	s_nop 1
	v_cndmask_b32_e32 v137, v229, v137, vcc
	v_lshlrev_b32_e32 v137, 2, v137
	ds_bpermute_b32 v137, v137, v135
	s_waitcnt lgkmcnt(0)
	v_add_f32_e32 v135, v135, v137
	v_xor_b32_e32 v137, 4, v229
	v_cmp_lt_i32_e32 vcc, v137, v136
	s_nop 1
	v_cndmask_b32_e32 v137, v229, v137, vcc
	v_lshlrev_b32_e32 v137, 2, v137
	ds_bpermute_b32 v137, v137, v135
	s_waitcnt lgkmcnt(0)
	v_add_f32_e32 v135, v135, v137
	v_xor_b32_e32 v137, 8, v229
	v_cmp_lt_i32_e32 vcc, v137, v136
	s_nop 1
	v_cndmask_b32_e32 v137, v229, v137, vcc
	v_lshlrev_b32_e32 v137, 2, v137
	ds_bpermute_b32 v137, v137, v135
	s_waitcnt lgkmcnt(0)
	v_add_f32_e32 v135, v135, v137
	v_xor_b32_e32 v137, 16, v229
	v_cmp_lt_i32_e32 vcc, v137, v136
	s_nop 1
	v_cndmask_b32_e32 v137, v229, v137, vcc
	v_lshlrev_b32_e32 v137, 2, v137
	ds_bpermute_b32 v137, v137, v135
	s_waitcnt lgkmcnt(0)
	v_add_f32_e32 v135, v135, v137
	v_xor_b32_e32 v137, 32, v229
	v_cmp_lt_i32_e32 vcc, v137, v136
	s_nop 1
	v_cndmask_b32_e32 v136, v229, v137, vcc
	v_lshlrev_b32_e32 v136, 2, v136
	ds_bpermute_b32 v136, v136, v135
	s_waitcnt lgkmcnt(0)
	v_add_f32_e32 v135, v135, v136
	v_fmamk_f32 v135, v135, 0x3a000000, v227
	v_cmp_gt_f32_e32 vcc, s96, v135
	v_mul_f32_e32 v136, 0x4b800000, v135
	s_nop 0
	v_cndmask_b32_e32 v135, v135, v136, vcc
	v_rsq_f32_e32 v135, v135
	s_nop 0
	v_mul_f32_e32 v136, 0x45800000, v135
	v_cndmask_b32_e32 v136, v135, v136, vcc
	v_pk_mul_f32 v[94:95], v[94:95], v[136:137] op_sel_hi:[1,0]
	v_pk_mul_f32 v[92:93], v[92:93], v[136:137] op_sel_hi:[1,0]
	v_pk_mul_f32 v[94:95], v[122:123], v[94:95]
	v_pk_mul_f32 v[92:93], v[120:121], v[92:93]
	v_pk_add_f32 v[120:121], v[126:127], 1.0 op_sel_hi:[1,0]
	v_pk_add_f32 v[122:123], v[124:125], 1.0 op_sel_hi:[1,0]
	v_pk_fma_f32 v[94:95], v[120:121], v[94:95], v[118:119]
	v_pk_fma_f32 v[92:93], v[122:123], v[92:93], v[116:117]
	v_pk_mul_f32 v[70:71], v[70:71], v[136:137] op_sel_hi:[1,0]
	v_pk_mul_f32 v[68:69], v[68:69], v[136:137] op_sel_hi:[1,0]
	v_cvt_pk_bf16_f32 v92, v92, v93
	v_cvt_pk_bf16_f32 v93, v94, v95
	v_pk_mul_f32 v[70:71], v[110:111], v[70:71]
	v_pk_mul_f32 v[68:69], v[108:109], v[68:69]
	v_pk_add_f32 v[94:95], v[114:115], 1.0 op_sel_hi:[1,0]
	v_pk_add_f32 v[108:109], v[112:113], 1.0 op_sel_hi:[1,0]
	v_pk_fma_f32 v[70:71], v[94:95], v[70:71], v[106:107]
	v_pk_fma_f32 v[68:69], v[108:109], v[68:69], v[104:105]
	v_pk_mul_f32 v[46:47], v[46:47], v[136:137] op_sel_hi:[1,0]
	v_pk_mul_f32 v[44:45], v[44:45], v[136:137] op_sel_hi:[1,0]
	v_cvt_pk_bf16_f32 v68, v68, v69
	v_cvt_pk_bf16_f32 v69, v70, v71
	v_pk_mul_f32 v[46:47], v[98:99], v[46:47]
	v_pk_mul_f32 v[44:45], v[96:97], v[44:45]
	v_pk_add_f32 v[70:71], v[102:103], 1.0 op_sel_hi:[1,0]
	v_pk_add_f32 v[94:95], v[100:101], 1.0 op_sel_hi:[1,0]
	v_pk_fma_f32 v[46:47], v[70:71], v[46:47], v[90:91]
	v_pk_fma_f32 v[44:45], v[94:95], v[44:45], v[88:89]
	v_pk_mul_f32 v[30:31], v[30:31], v[136:137] op_sel_hi:[1,0]
	v_pk_mul_f32 v[28:29], v[28:29], v[136:137] op_sel_hi:[1,0]
	v_cvt_pk_bf16_f32 v44, v44, v45
	v_cvt_pk_bf16_f32 v45, v46, v47
	v_pk_mul_f32 v[30:31], v[82:83], v[30:31]
	v_pk_mul_f32 v[28:29], v[80:81], v[28:29]
	v_pk_add_f32 v[46:47], v[86:87], 1.0 op_sel_hi:[1,0]
	v_pk_add_f32 v[70:71], v[84:85], 1.0 op_sel_hi:[1,0]
	v_pk_fma_f32 v[30:31], v[46:47], v[30:31], v[74:75]
	v_pk_fma_f32 v[28:29], v[70:71], v[28:29], v[72:73]
	v_pk_mul_f32 v[14:15], v[14:15], v[136:137] op_sel_hi:[1,0]
	v_pk_mul_f32 v[12:13], v[12:13], v[136:137] op_sel_hi:[1,0]
	v_cvt_pk_bf16_f32 v28, v28, v29
	v_cvt_pk_bf16_f32 v29, v30, v31
	v_pk_mul_f32 v[14:15], v[66:67], v[14:15]
	v_pk_mul_f32 v[12:13], v[64:65], v[12:13]
	v_pk_add_f32 v[30:31], v[78:79], 1.0 op_sel_hi:[1,0]
	v_pk_add_f32 v[46:47], v[76:77], 1.0 op_sel_hi:[1,0]
	v_pk_fma_f32 v[14:15], v[30:31], v[14:15], v[62:63]
	v_pk_fma_f32 v[12:13], v[46:47], v[12:13], v[60:61]
	v_pk_mul_f32 v[10:11], v[10:11], v[136:137] op_sel_hi:[1,0]
	v_pk_mul_f32 v[8:9], v[8:9], v[136:137] op_sel_hi:[1,0]
	v_cvt_pk_bf16_f32 v12, v12, v13
	v_cvt_pk_bf16_f32 v13, v14, v15
	v_pk_mul_f32 v[10:11], v[54:55], v[10:11]
	v_pk_mul_f32 v[8:9], v[52:53], v[8:9]
	v_pk_add_f32 v[14:15], v[58:59], 1.0 op_sel_hi:[1,0]
	v_pk_add_f32 v[30:31], v[56:57], 1.0 op_sel_hi:[1,0]
	v_pk_fma_f32 v[10:11], v[14:15], v[10:11], v[50:51]
	v_pk_fma_f32 v[8:9], v[30:31], v[8:9], v[48:49]
	v_pk_mul_f32 v[6:7], v[6:7], v[136:137] op_sel_hi:[1,0]
	v_pk_mul_f32 v[4:5], v[4:5], v[136:137] op_sel_hi:[1,0]
	v_cvt_pk_bf16_f32 v8, v8, v9
	v_cvt_pk_bf16_f32 v9, v10, v11
	v_pk_mul_f32 v[6:7], v[38:39], v[6:7]
	v_pk_mul_f32 v[4:5], v[36:37], v[4:5]
	v_pk_add_f32 v[10:11], v[42:43], 1.0 op_sel_hi:[1,0]
	v_pk_add_f32 v[14:15], v[40:41], 1.0 op_sel_hi:[1,0]
	v_pk_fma_f32 v[6:7], v[10:11], v[6:7], v[34:35]
	v_pk_fma_f32 v[4:5], v[14:15], v[4:5], v[32:33]
	v_pk_mul_f32 v[2:3], v[2:3], v[136:137] op_sel_hi:[1,0]
	v_pk_mul_f32 v[0:1], v[0:1], v[136:137] op_sel_hi:[1,0]
	v_cvt_pk_bf16_f32 v4, v4, v5
	v_cvt_pk_bf16_f32 v5, v6, v7
	v_pk_mul_f32 v[2:3], v[22:23], v[2:3]
	v_pk_mul_f32 v[0:1], v[20:21], v[0:1]
	v_pk_add_f32 v[6:7], v[26:27], 1.0 op_sel_hi:[1,0]
	v_pk_add_f32 v[10:11], v[24:25], 1.0 op_sel_hi:[1,0]
	v_pk_fma_f32 v[2:3], v[6:7], v[2:3], v[18:19]
	v_pk_fma_f32 v[0:1], v[10:11], v[0:1], v[16:17]
	v_cmp_lt_i32_e32 vcc, s2, v128
	v_cvt_pk_bf16_f32 v0, v0, v1
	v_cvt_pk_bf16_f32 v1, v2, v3
	v_lshl_add_u64 v[2:3], v[132:133], 1, v[130:131]
	v_lshl_add_u64 v[130:131], v[130:131], 0, s[76:77]
	s_or_b64 s[12:13], vcc, s[12:13]
	global_store_dwordx2 v[2:3], v[92:93], off
	global_store_dwordx2 v[2:3], v[68:69], off offset:512
	global_store_dwordx2 v[2:3], v[44:45], off offset:1024
	global_store_dwordx2 v[2:3], v[28:29], off offset:1536
	global_store_dwordx2 v[2:3], v[12:13], off offset:2048
	global_store_dwordx2 v[2:3], v[8:9], off offset:2560
	global_store_dwordx2 v[2:3], v[4:5], off offset:3072
	global_store_dwordx2 v[2:3], v[0:1], off offset:3584
	s_andn2_b64 exec, exec, s[12:13]
	s_cbranch_execnz .LBB0_82

.LBB0_281:
	s_cmpk_gt_i32 s5, 0x3ff
	s_mov_b64 s[0:1], -1
	s_cbranch_scc0 .LBB0_283
	s_and_b32 s0, s4, 0x7fffff00
	s_add_i32 s64, s0, 0xffffe000
	s_and_b32 s0, s3, 0x7c0
	v_mov_b32_e32 v33, v224
	s_lshl_b32 s1, s0, 2
	v_lshlrev_b32_e32 v0, 4, v33
	v_ashrrev_i32_e32 v34, 4, v33
	v_add_u32_e32 v4, 0x200, v33
	s_add_u32 s14, s55, s1
	v_and_b32_e32 v192, 0xf0, v0
	v_add_u32_e32 v0, s64, v34
	v_ashrrev_i32_e32 v36, 4, v4
	v_add_u32_e32 v8, 0x400, v33
	s_addc_u32 s15, s58, 0
	s_waitcnt lgkmcnt(0)
	v_ashrrev_i32_e32 v1, 31, v0
	v_add_u32_e32 v4, s64, v36
	v_ashrrev_i32_e32 v37, 4, v8
	v_add_u32_e32 v12, 0x600, v33
	v_lshl_add_u64 v[28:29], s[14:15], 0, v[192:193]
	v_lshlrev_b64 v[0:1], 13, v[0:1]
	v_ashrrev_i32_e32 v5, 31, v4
	v_add_u32_e32 v8, s64, v37
	v_ashrrev_i32_e32 v38, 4, v12
	v_add_u32_e32 v16, 0x800, v33
	v_lshl_add_u64 v[0:1], v[28:29], 0, v[0:1]
	v_lshlrev_b64 v[4:5], 13, v[4:5]
	v_ashrrev_i32_e32 v9, 31, v8
	v_add_u32_e32 v12, s64, v38
	v_ashrrev_i32_e32 v39, 4, v16
	v_add_u32_e32 v20, 0xa00, v33
	global_load_dwordx4 v[0:3], v[0:1], off nt
	v_lshl_add_u64 v[4:5], v[28:29], 0, v[4:5]
	v_lshlrev_b64 v[8:9], 13, v[8:9]
	v_ashrrev_i32_e32 v13, 31, v12
	v_add_u32_e32 v16, s64, v39
	v_ashrrev_i32_e32 v40, 4, v20
	v_add_u32_e32 v24, 0xc00, v33
	global_load_dwordx4 v[4:7], v[4:5], off nt
	v_lshl_add_u64 v[8:9], v[28:29], 0, v[8:9]
	v_lshlrev_b64 v[12:13], 13, v[12:13]
	v_ashrrev_i32_e32 v17, 31, v16
	v_add_u32_e32 v20, s64, v40
	v_ashrrev_i32_e32 v41, 4, v24
	v_add_u32_e32 v30, 0xe00, v33
	global_load_dwordx4 v[8:11], v[8:9], off nt
	v_lshl_add_u64 v[12:13], v[28:29], 0, v[12:13]
	v_lshlrev_b64 v[16:17], 13, v[16:17]
	v_ashrrev_i32_e32 v21, 31, v20
	v_add_u32_e32 v24, s64, v41
	v_ashrrev_i32_e32 v42, 4, v30
	global_load_dwordx4 v[12:15], v[12:13], off nt
	v_lshl_add_u64 v[16:17], v[28:29], 0, v[16:17]
	v_lshlrev_b64 v[20:21], 13, v[20:21]
	v_ashrrev_i32_e32 v25, 31, v24
	v_add_u32_e32 v30, s64, v42
	global_load_dwordx4 v[16:19], v[16:17], off nt
	v_lshl_add_u64 v[20:21], v[28:29], 0, v[20:21]
	v_lshlrev_b64 v[24:25], 13, v[24:25]
	v_ashrrev_i32_e32 v31, 31, v30
	global_load_dwordx4 v[20:23], v[20:21], off nt
	v_lshl_add_u64 v[24:25], v[28:29], 0, v[24:25]
	v_lshlrev_b64 v[30:31], 13, v[30:31]
	global_load_dwordx4 v[24:27], v[24:25], off nt
	v_lshl_add_u64 v[28:29], v[28:29], 0, v[30:31]
	global_load_dwordx4 v[28:31], v[28:29], off nt
	v_add_u32_e32 v32, 0, v192
	v_mad_u64_u32 v[34:35], s[14:15], v34, s97, v[32:33]
	s_waitcnt vmcnt(0)
	ds_write2_b32 v34, v0, v1 offset1:1
	ds_write2_b32 v34, v2, v3 offset0:2 offset1:3
	v_mad_u64_u32 v[0:1], s[14:15], v36, s97, v[32:33]
	ds_write2_b32 v0, v4, v5 offset1:1
	ds_write2_b32 v0, v6, v7 offset0:2 offset1:3
	v_mad_u64_u32 v[0:1], s[14:15], v37, s97, v[32:33]
	ds_write2_b32 v0, v8, v9 offset1:1
	ds_write2_b32 v0, v10, v11 offset0:2 offset1:3
	v_mad_u64_u32 v[0:1], s[14:15], v38, s97, v[32:33]
	ds_write2_b32 v0, v12, v13 offset1:1
	ds_write2_b32 v0, v14, v15 offset0:2 offset1:3
	v_mad_u64_u32 v[0:1], s[14:15], v39, s97, v[32:33]
	ds_write2_b32 v0, v16, v17 offset1:1
	ds_write2_b32 v0, v18, v19 offset0:2 offset1:3
	v_mad_u64_u32 v[0:1], s[14:15], v40, s97, v[32:33]
	ds_write2_b32 v0, v20, v21 offset1:1
	ds_write2_b32 v0, v22, v23 offset0:2 offset1:3
	v_mad_u64_u32 v[0:1], s[14:15], v41, s97, v[32:33]
	ds_write2_b32 v0, v24, v25 offset1:1
	ds_write2_b32 v0, v26, v27 offset0:2 offset1:3
	v_mad_u64_u32 v[0:1], s[14:15], v42, s97, v[32:33]
	v_ashrrev_i32_e32 v2, 3, v33
	ds_write2_b32 v0, v28, v29 offset1:1
	ds_write2_b32 v0, v30, v31 offset0:2 offset1:3
	v_add_u32_e32 v0, s0, v2
	v_lshlrev_b32_e32 v3, 3, v33
	v_ashrrev_i32_e32 v1, 31, v0
	v_and_b32_e32 v3, 56, v3
	v_lshlrev_b32_e32 v2, 2, v2
	v_mul_u32_u24_e32 v4, 0x104, v3
	v_lshlrev_b64 v[0:1], 14, v[0:1]
	v_add3_u32 v32, 0, v2, v4
	v_lshl_add_u64 v[0:1], s[62:63], 0, v[0:1]
	v_lshl_add_u64 v[0:1], s[64:65], 1, v[0:1]
	v_lshlrev_b32_e32 v192, 1, v3
	v_add_u32_e32 v8, 0x400, v32
	s_waitcnt lgkmcnt(0)
	s_barrier
	v_lshl_add_u64 v[4:5], v[0:1], 0, v[192:193]
	ds_read2_b32 v[0:1], v32 offset1:65
	ds_read2_b32 v[2:3], v32 offset0:130 offset1:195
	ds_read2_b32 v[6:7], v8 offset0:4 offset1:69
	ds_read2_b32 v[8:9], v8 offset0:134 offset1:199
	v_add_u32_e32 v10, 0x4000, v32
	v_add_u32_e32 v12, 0x4200, v32
	v_add_u32_e32 v14, 0x4400, v32
	v_add_u32_e32 v16, 0x4600, v32
	v_add_u32_e32 v18, 0x8000, v32
	v_add_u32_e32 v22, 0x8400, v32
	ds_read2_b32 v[10:11], v10 offset0:64 offset1:129
	ds_read2_b32 v[12:13], v12 offset0:66 offset1:131
	ds_read2_b32 v[14:15], v14 offset0:68 offset1:133
	ds_read2_b32 v[16:17], v16 offset0:70 offset1:135
	ds_read2_b32 v[18:19], v18 offset0:128 offset1:193
	ds_read2_b32 v[20:21], v22 offset0:2 offset1:67
	ds_read2_b32 v[22:23], v22 offset0:132 offset1:197
	v_add_u32_e32 v24, 0x8800, v32
	v_add_u32_e32 v26, 0xc200, v32
	v_add_u32_e32 v28, 0xc400, v32
	v_add_u32_e32 v30, 0xc600, v32
	v_add_u32_e32 v32, 0xc800, v32
	ds_read2_b32 v[24:25], v24 offset0:6 offset1:71
	ds_read2_b32 v[26:27], v26 offset0:64 offset1:129
	ds_read2_b32 v[28:29], v28 offset0:66 offset1:131
	ds_read2_b32 v[30:31], v30 offset0:68 offset1:133
	ds_read2_b32 v[32:33], v32 offset0:70 offset1:135
	s_waitcnt lgkmcnt(14)
	v_cvt_pk_bf16_f32 v0, v0, v1
	v_cvt_pk_bf16_f32 v1, v2, v3
	s_waitcnt lgkmcnt(13)
	v_cvt_pk_bf16_f32 v2, v6, v7
	s_waitcnt lgkmcnt(12)
	v_cvt_pk_bf16_f32 v3, v8, v9
	global_store_dwordx4 v[4:5], v[0:3], off nt
	s_mov_b64 s[0:1], 0
	s_waitcnt lgkmcnt(11)
	v_cvt_pk_bf16_f32 v0, v10, v11
	s_waitcnt lgkmcnt(10)
	v_cvt_pk_bf16_f32 v1, v12, v13
	s_waitcnt lgkmcnt(9)
	v_cvt_pk_bf16_f32 v2, v14, v15
	s_waitcnt lgkmcnt(8)
	v_cvt_pk_bf16_f32 v3, v16, v17
	global_store_dwordx4 v[4:5], v[0:3], off offset:128 nt
	s_waitcnt lgkmcnt(7)
	s_nop 0
	v_cvt_pk_bf16_f32 v0, v18, v19
	s_waitcnt lgkmcnt(6)
	v_cvt_pk_bf16_f32 v1, v20, v21
	s_waitcnt lgkmcnt(5)
	v_cvt_pk_bf16_f32 v2, v22, v23
	s_waitcnt lgkmcnt(4)
	v_cvt_pk_bf16_f32 v3, v24, v25
	global_store_dwordx4 v[4:5], v[0:3], off offset:256 nt
	s_waitcnt lgkmcnt(3)
	s_nop 0
	v_cvt_pk_bf16_f32 v0, v26, v27
	s_waitcnt lgkmcnt(2)
	v_cvt_pk_bf16_f32 v1, v28, v29
	s_waitcnt lgkmcnt(1)
	v_cvt_pk_bf16_f32 v2, v30, v31
	s_waitcnt lgkmcnt(0)
	v_cvt_pk_bf16_f32 v3, v32, v33
	global_store_dwordx4 v[4:5], v[0:3], off offset:384 nt
	s_barrier
.LBB0_283:
	s_andn2_b64 vcc, exec, s[0:1]
	s_cbranch_vccnz .LBB0_280
	s_and_b32 s1, s3, 0x1fc0
	v_mov_b32_e32 v33, v224
	s_and_b32 s0, s2, 0xffffff00
	s_lshl_b32 s9, s1, 2
	v_readlane_b32 s14, v252, 20
	v_lshlrev_b32_e32 v0, 4, v33
	v_ashrrev_i32_e32 v34, 4, v33
	v_add_u32_e32 v4, 0x200, v33
	s_add_u32 s14, s14, s9
	v_readlane_b32 s9, v252, 21
	v_and_b32_e32 v192, 0xf0, v0
	v_add_u32_e32 v0, s0, v34
	v_ashrrev_i32_e32 v36, 4, v4
	v_add_u32_e32 v8, 0x400, v33
	s_addc_u32 s15, s9, 0
	s_waitcnt lgkmcnt(0)
	v_ashrrev_i32_e32 v1, 31, v0
	v_add_u32_e32 v4, s0, v36
	v_ashrrev_i32_e32 v37, 4, v8
	v_add_u32_e32 v12, 0x600, v33
	v_lshl_add_u64 v[28:29], s[14:15], 0, v[192:193]
	v_lshlrev_b64 v[0:1], 15, v[0:1]
	v_ashrrev_i32_e32 v5, 31, v4
	v_add_u32_e32 v8, s0, v37
	v_ashrrev_i32_e32 v38, 4, v12
	v_add_u32_e32 v16, 0x800, v33
	v_lshl_add_u64 v[0:1], v[28:29], 0, v[0:1]
	v_lshlrev_b64 v[4:5], 15, v[4:5]
	v_ashrrev_i32_e32 v9, 31, v8
	v_add_u32_e32 v12, s0, v38
	v_ashrrev_i32_e32 v39, 4, v16
	v_add_u32_e32 v20, 0xa00, v33
	global_load_dwordx4 v[0:3], v[0:1], off nt
	v_lshl_add_u64 v[4:5], v[28:29], 0, v[4:5]
	v_lshlrev_b64 v[8:9], 15, v[8:9]
	v_ashrrev_i32_e32 v13, 31, v12
	v_add_u32_e32 v16, s0, v39
	v_ashrrev_i32_e32 v40, 4, v20
	v_add_u32_e32 v24, 0xc00, v33
	global_load_dwordx4 v[4:7], v[4:5], off nt
	v_lshl_add_u64 v[8:9], v[28:29], 0, v[8:9]
	v_lshlrev_b64 v[12:13], 15, v[12:13]
	v_ashrrev_i32_e32 v17, 31, v16
	v_add_u32_e32 v20, s0, v40
	v_ashrrev_i32_e32 v41, 4, v24
	v_add_u32_e32 v30, 0xe00, v33
	global_load_dwordx4 v[8:11], v[8:9], off nt
	v_lshl_add_u64 v[12:13], v[28:29], 0, v[12:13]
	v_lshlrev_b64 v[16:17], 15, v[16:17]
	v_ashrrev_i32_e32 v21, 31, v20
	v_add_u32_e32 v24, s0, v41
	v_ashrrev_i32_e32 v42, 4, v30
	global_load_dwordx4 v[12:15], v[12:13], off nt
	v_lshl_add_u64 v[16:17], v[28:29], 0, v[16:17]
	v_lshlrev_b64 v[20:21], 15, v[20:21]
	v_ashrrev_i32_e32 v25, 31, v24
	v_add_u32_e32 v30, s0, v42
	global_load_dwordx4 v[16:19], v[16:17], off nt
	v_lshl_add_u64 v[20:21], v[28:29], 0, v[20:21]
	v_lshlrev_b64 v[24:25], 15, v[24:25]
	v_ashrrev_i32_e32 v31, 31, v30
	global_load_dwordx4 v[20:23], v[20:21], off nt
	v_lshl_add_u64 v[24:25], v[28:29], 0, v[24:25]
	v_lshlrev_b64 v[30:31], 15, v[30:31]
	global_load_dwordx4 v[24:27], v[24:25], off nt
	v_lshl_add_u64 v[28:29], v[28:29], 0, v[30:31]
	global_load_dwordx4 v[28:31], v[28:29], off nt
	v_add_u32_e32 v32, 0, v192
	v_mad_u64_u32 v[34:35], s[14:15], v34, s97, v[32:33]
	s_waitcnt vmcnt(0)
	ds_write2_b32 v34, v0, v1 offset1:1
	ds_write2_b32 v34, v2, v3 offset0:2 offset1:3
	v_mad_u64_u32 v[0:1], s[14:15], v36, s97, v[32:33]
	ds_write2_b32 v0, v4, v5 offset1:1
	ds_write2_b32 v0, v6, v7 offset0:2 offset1:3
	v_mad_u64_u32 v[0:1], s[14:15], v37, s97, v[32:33]
	ds_write2_b32 v0, v8, v9 offset1:1
	ds_write2_b32 v0, v10, v11 offset0:2 offset1:3
	v_mad_u64_u32 v[0:1], s[14:15], v38, s97, v[32:33]
	ds_write2_b32 v0, v12, v13 offset1:1
	ds_write2_b32 v0, v14, v15 offset0:2 offset1:3
	v_mad_u64_u32 v[0:1], s[14:15], v39, s97, v[32:33]
	ds_write2_b32 v0, v16, v17 offset1:1
	ds_write2_b32 v0, v18, v19 offset0:2 offset1:3
	v_mad_u64_u32 v[0:1], s[14:15], v40, s97, v[32:33]
	ds_write2_b32 v0, v20, v21 offset1:1
	ds_write2_b32 v0, v22, v23 offset0:2 offset1:3
	v_mad_u64_u32 v[0:1], s[14:15], v41, s97, v[32:33]
	ds_write2_b32 v0, v24, v25 offset1:1
	ds_write2_b32 v0, v26, v27 offset0:2 offset1:3
	v_mad_u64_u32 v[0:1], s[14:15], v42, s97, v[32:33]
	v_ashrrev_i32_e32 v2, 3, v33
	ds_write2_b32 v0, v28, v29 offset1:1
	ds_write2_b32 v0, v30, v31 offset0:2 offset1:3
	v_add_u32_e32 v0, s1, v2
	v_lshlrev_b32_e32 v3, 3, v33
	v_ashrrev_i32_e32 v1, 31, v0
	v_and_b32_e32 v3, 56, v3
	v_readlane_b32 s14, v252, 22
	v_lshlrev_b32_e32 v2, 2, v2
	v_mul_u32_u24_e32 v4, 0x104, v3
	v_lshlrev_b64 v[0:1], 12, v[0:1]
	v_readlane_b32 s15, v252, 23
	s_ashr_i32 s1, s0, 31
	v_add3_u32 v32, 0, v2, v4
	v_lshl_add_u64 v[0:1], s[14:15], 0, v[0:1]
	v_lshl_add_u64 v[0:1], s[0:1], 1, v[0:1]
	v_lshlrev_b32_e32 v192, 1, v3
	v_add_u32_e32 v8, 0x400, v32
	s_waitcnt lgkmcnt(0)
	s_barrier
	v_lshl_add_u64 v[4:5], v[0:1], 0, v[192:193]
	ds_read2_b32 v[0:1], v32 offset1:65
	ds_read2_b32 v[2:3], v32 offset0:130 offset1:195
	ds_read2_b32 v[6:7], v8 offset0:4 offset1:69
	ds_read2_b32 v[8:9], v8 offset0:134 offset1:199
	v_add_u32_e32 v10, 0x4000, v32
	v_add_u32_e32 v12, 0x4200, v32
	v_add_u32_e32 v14, 0x4400, v32
	v_add_u32_e32 v16, 0x4600, v32
	v_add_u32_e32 v18, 0x8000, v32
	v_add_u32_e32 v22, 0x8400, v32
	ds_read2_b32 v[10:11], v10 offset0:64 offset1:129
	ds_read2_b32 v[12:13], v12 offset0:66 offset1:131
	ds_read2_b32 v[14:15], v14 offset0:68 offset1:133
	ds_read2_b32 v[16:17], v16 offset0:70 offset1:135
	ds_read2_b32 v[18:19], v18 offset0:128 offset1:193
	ds_read2_b32 v[20:21], v22 offset0:2 offset1:67
	ds_read2_b32 v[22:23], v22 offset0:132 offset1:197
	v_add_u32_e32 v24, 0x8800, v32
	v_add_u32_e32 v26, 0xc200, v32
	v_add_u32_e32 v28, 0xc400, v32
	v_add_u32_e32 v30, 0xc600, v32
	v_add_u32_e32 v32, 0xc800, v32
	ds_read2_b32 v[24:25], v24 offset0:6 offset1:71
	ds_read2_b32 v[26:27], v26 offset0:64 offset1:129
	ds_read2_b32 v[28:29], v28 offset0:66 offset1:131
	ds_read2_b32 v[30:31], v30 offset0:68 offset1:133
	ds_read2_b32 v[32:33], v32 offset0:70 offset1:135
	s_waitcnt lgkmcnt(14)
	v_cvt_pk_bf16_f32 v0, v0, v1
	v_cvt_pk_bf16_f32 v1, v2, v3
	s_waitcnt lgkmcnt(13)
	v_cvt_pk_bf16_f32 v2, v6, v7
	s_waitcnt lgkmcnt(12)
	v_cvt_pk_bf16_f32 v3, v8, v9
	global_store_dwordx4 v[4:5], v[0:3], off nt
	s_waitcnt lgkmcnt(11)
	s_nop 0
	v_cvt_pk_bf16_f32 v0, v10, v11
	s_waitcnt lgkmcnt(10)
	v_cvt_pk_bf16_f32 v1, v12, v13
	s_waitcnt lgkmcnt(9)
	v_cvt_pk_bf16_f32 v2, v14, v15
	s_waitcnt lgkmcnt(8)
	v_cvt_pk_bf16_f32 v3, v16, v17
	global_store_dwordx4 v[4:5], v[0:3], off offset:128 nt
	s_waitcnt lgkmcnt(7)
	s_nop 0
	v_cvt_pk_bf16_f32 v0, v18, v19
	s_waitcnt lgkmcnt(6)
	v_cvt_pk_bf16_f32 v1, v20, v21
	s_waitcnt lgkmcnt(5)
	v_cvt_pk_bf16_f32 v2, v22, v23
	s_waitcnt lgkmcnt(4)
	v_cvt_pk_bf16_f32 v3, v24, v25
	global_store_dwordx4 v[4:5], v[0:3], off offset:256 nt
	s_waitcnt lgkmcnt(3)
	s_nop 0
	v_cvt_pk_bf16_f32 v0, v26, v27
	s_waitcnt lgkmcnt(2)
	v_cvt_pk_bf16_f32 v1, v28, v29
	s_waitcnt lgkmcnt(1)
	v_cvt_pk_bf16_f32 v2, v30, v31
	s_waitcnt lgkmcnt(0)
	v_cvt_pk_bf16_f32 v3, v32, v33
	global_store_dwordx4 v[4:5], v[0:3], off offset:384 nt
	s_barrier
	s_branch .LBB0_280

.LBB0_286:
	s_addk_i32 s2, 0x80
	s_cmpk_gt_i32 s2, 0x3ff
	s_mov_b64 s[0:1], -1
	s_cbranch_scc0 .LBB0_288
	s_and_b32 s0, s5, 0x7fffff00
	s_add_i32 s64, s0, 0xffffe000
	s_and_b32 s0, s4, 0x7c0
	v_mov_b32_e32 v33, v224
	s_lshl_b32 s1, s0, 2
	v_lshlrev_b32_e32 v0, 4, v33
	v_ashrrev_i32_e32 v34, 4, v33
	v_add_u32_e32 v4, 0x200, v33
	s_add_u32 s14, s55, s1
	v_and_b32_e32 v192, 0xf0, v0
	v_add_u32_e32 v0, s64, v34
	v_ashrrev_i32_e32 v36, 4, v4
	v_add_u32_e32 v8, 0x400, v33
	s_addc_u32 s15, s58, 0
	s_waitcnt lgkmcnt(0)
	v_ashrrev_i32_e32 v1, 31, v0
	v_add_u32_e32 v4, s64, v36
	v_ashrrev_i32_e32 v37, 4, v8
	v_add_u32_e32 v12, 0x600, v33
	v_lshl_add_u64 v[28:29], s[14:15], 0, v[192:193]
	v_lshlrev_b64 v[0:1], 13, v[0:1]
	v_ashrrev_i32_e32 v5, 31, v4
	v_add_u32_e32 v8, s64, v37
	v_ashrrev_i32_e32 v38, 4, v12
	v_add_u32_e32 v16, 0x800, v33
	v_lshl_add_u64 v[0:1], v[28:29], 0, v[0:1]
	v_lshlrev_b64 v[4:5], 13, v[4:5]
	v_ashrrev_i32_e32 v9, 31, v8
	v_add_u32_e32 v12, s64, v38
	v_ashrrev_i32_e32 v39, 4, v16
	v_add_u32_e32 v20, 0xa00, v33
	global_load_dwordx4 v[0:3], v[0:1], off nt
	v_lshl_add_u64 v[4:5], v[28:29], 0, v[4:5]
	v_lshlrev_b64 v[8:9], 13, v[8:9]
	v_ashrrev_i32_e32 v13, 31, v12
	v_add_u32_e32 v16, s64, v39
	v_ashrrev_i32_e32 v40, 4, v20
	v_add_u32_e32 v24, 0xc00, v33
	global_load_dwordx4 v[4:7], v[4:5], off nt
	v_lshl_add_u64 v[8:9], v[28:29], 0, v[8:9]
	v_lshlrev_b64 v[12:13], 13, v[12:13]
	v_ashrrev_i32_e32 v17, 31, v16
	v_add_u32_e32 v20, s64, v40
	v_ashrrev_i32_e32 v41, 4, v24
	v_add_u32_e32 v30, 0xe00, v33
	global_load_dwordx4 v[8:11], v[8:9], off nt
	v_lshl_add_u64 v[12:13], v[28:29], 0, v[12:13]
	v_lshlrev_b64 v[16:17], 13, v[16:17]
	v_ashrrev_i32_e32 v21, 31, v20
	v_add_u32_e32 v24, s64, v41
	v_ashrrev_i32_e32 v42, 4, v30
	global_load_dwordx4 v[12:15], v[12:13], off nt
	v_lshl_add_u64 v[16:17], v[28:29], 0, v[16:17]
	v_lshlrev_b64 v[20:21], 13, v[20:21]
	v_ashrrev_i32_e32 v25, 31, v24
	v_add_u32_e32 v30, s64, v42
	global_load_dwordx4 v[16:19], v[16:17], off nt
	v_lshl_add_u64 v[20:21], v[28:29], 0, v[20:21]
	v_lshlrev_b64 v[24:25], 13, v[24:25]
	v_ashrrev_i32_e32 v31, 31, v30
	global_load_dwordx4 v[20:23], v[20:21], off nt
	v_lshl_add_u64 v[24:25], v[28:29], 0, v[24:25]
	v_lshlrev_b64 v[30:31], 13, v[30:31]
	global_load_dwordx4 v[24:27], v[24:25], off nt
	v_lshl_add_u64 v[28:29], v[28:29], 0, v[30:31]
	global_load_dwordx4 v[28:31], v[28:29], off nt
	v_add_u32_e32 v32, 0, v192
	v_mad_u64_u32 v[34:35], s[14:15], v34, s97, v[32:33]
	s_waitcnt vmcnt(0)
	ds_write2_b32 v34, v0, v1 offset1:1
	ds_write2_b32 v34, v2, v3 offset0:2 offset1:3
	v_mad_u64_u32 v[0:1], s[14:15], v36, s97, v[32:33]
	ds_write2_b32 v0, v4, v5 offset1:1
	ds_write2_b32 v0, v6, v7 offset0:2 offset1:3
	v_mad_u64_u32 v[0:1], s[14:15], v37, s97, v[32:33]
	ds_write2_b32 v0, v8, v9 offset1:1
	ds_write2_b32 v0, v10, v11 offset0:2 offset1:3
	v_mad_u64_u32 v[0:1], s[14:15], v38, s97, v[32:33]
	ds_write2_b32 v0, v12, v13 offset1:1
	ds_write2_b32 v0, v14, v15 offset0:2 offset1:3
	v_mad_u64_u32 v[0:1], s[14:15], v39, s97, v[32:33]
	ds_write2_b32 v0, v16, v17 offset1:1
	ds_write2_b32 v0, v18, v19 offset0:2 offset1:3
	v_mad_u64_u32 v[0:1], s[14:15], v40, s97, v[32:33]
	ds_write2_b32 v0, v20, v21 offset1:1
	ds_write2_b32 v0, v22, v23 offset0:2 offset1:3
	v_mad_u64_u32 v[0:1], s[14:15], v41, s97, v[32:33]
	ds_write2_b32 v0, v24, v25 offset1:1
	ds_write2_b32 v0, v26, v27 offset0:2 offset1:3
	v_mad_u64_u32 v[0:1], s[14:15], v42, s97, v[32:33]
	v_ashrrev_i32_e32 v2, 3, v33
	ds_write2_b32 v0, v28, v29 offset1:1
	ds_write2_b32 v0, v30, v31 offset0:2 offset1:3
	v_add_u32_e32 v0, s0, v2
	v_lshlrev_b32_e32 v3, 3, v33
	v_ashrrev_i32_e32 v1, 31, v0
	v_and_b32_e32 v3, 56, v3
	v_lshlrev_b32_e32 v2, 2, v2
	v_mul_u32_u24_e32 v4, 0x104, v3
	v_lshlrev_b64 v[0:1], 14, v[0:1]
	v_add3_u32 v32, 0, v2, v4
	v_lshl_add_u64 v[0:1], s[62:63], 0, v[0:1]
	v_lshl_add_u64 v[0:1], s[64:65], 1, v[0:1]
	v_lshlrev_b32_e32 v192, 1, v3
	v_add_u32_e32 v8, 0x400, v32
	s_waitcnt lgkmcnt(0)
	s_barrier
	v_lshl_add_u64 v[4:5], v[0:1], 0, v[192:193]
	ds_read2_b32 v[0:1], v32 offset1:65
	ds_read2_b32 v[2:3], v32 offset0:130 offset1:195
	ds_read2_b32 v[6:7], v8 offset0:4 offset1:69
	ds_read2_b32 v[8:9], v8 offset0:134 offset1:199
	v_add_u32_e32 v10, 0x4000, v32
	v_add_u32_e32 v12, 0x4200, v32
	v_add_u32_e32 v14, 0x4400, v32
	v_add_u32_e32 v16, 0x4600, v32
	v_add_u32_e32 v18, 0x8000, v32
	v_add_u32_e32 v22, 0x8400, v32
	ds_read2_b32 v[10:11], v10 offset0:64 offset1:129
	ds_read2_b32 v[12:13], v12 offset0:66 offset1:131
	ds_read2_b32 v[14:15], v14 offset0:68 offset1:133
	ds_read2_b32 v[16:17], v16 offset0:70 offset1:135
	ds_read2_b32 v[18:19], v18 offset0:128 offset1:193
	ds_read2_b32 v[20:21], v22 offset0:2 offset1:67
	ds_read2_b32 v[22:23], v22 offset0:132 offset1:197
	v_add_u32_e32 v24, 0x8800, v32
	v_add_u32_e32 v26, 0xc200, v32
	v_add_u32_e32 v28, 0xc400, v32
	v_add_u32_e32 v30, 0xc600, v32
	v_add_u32_e32 v32, 0xc800, v32
	ds_read2_b32 v[24:25], v24 offset0:6 offset1:71
	ds_read2_b32 v[26:27], v26 offset0:64 offset1:129
	ds_read2_b32 v[28:29], v28 offset0:66 offset1:131
	ds_read2_b32 v[30:31], v30 offset0:68 offset1:133
	ds_read2_b32 v[32:33], v32 offset0:70 offset1:135
	s_waitcnt lgkmcnt(14)
	v_cvt_pk_bf16_f32 v0, v0, v1
	v_cvt_pk_bf16_f32 v1, v2, v3
	s_waitcnt lgkmcnt(13)
	v_cvt_pk_bf16_f32 v2, v6, v7
	s_waitcnt lgkmcnt(12)
	v_cvt_pk_bf16_f32 v3, v8, v9
	global_store_dwordx4 v[4:5], v[0:3], off nt
	s_mov_b64 s[0:1], 0
	s_waitcnt lgkmcnt(11)
	v_cvt_pk_bf16_f32 v0, v10, v11
	s_waitcnt lgkmcnt(10)
	v_cvt_pk_bf16_f32 v1, v12, v13
	s_waitcnt lgkmcnt(9)
	v_cvt_pk_bf16_f32 v2, v14, v15
	s_waitcnt lgkmcnt(8)
	v_cvt_pk_bf16_f32 v3, v16, v17
	global_store_dwordx4 v[4:5], v[0:3], off offset:128 nt
	s_waitcnt lgkmcnt(7)
	s_nop 0
	v_cvt_pk_bf16_f32 v0, v18, v19
	s_waitcnt lgkmcnt(6)
	v_cvt_pk_bf16_f32 v1, v20, v21
	s_waitcnt lgkmcnt(5)
	v_cvt_pk_bf16_f32 v2, v22, v23
	s_waitcnt lgkmcnt(4)
	v_cvt_pk_bf16_f32 v3, v24, v25
	global_store_dwordx4 v[4:5], v[0:3], off offset:256 nt
	s_waitcnt lgkmcnt(3)
	s_nop 0
	v_cvt_pk_bf16_f32 v0, v26, v27
	s_waitcnt lgkmcnt(2)
	v_cvt_pk_bf16_f32 v1, v28, v29
	s_waitcnt lgkmcnt(1)
	v_cvt_pk_bf16_f32 v2, v30, v31
	s_waitcnt lgkmcnt(0)
	v_cvt_pk_bf16_f32 v3, v32, v33
	global_store_dwordx4 v[4:5], v[0:3], off offset:384 nt
	s_barrier
.LBB0_288:
	s_andn2_b64 vcc, exec, s[0:1]
	s_cbranch_vccnz .LBB0_285
	s_and_b32 s1, s4, 0x1fc0
	v_mov_b32_e32 v33, v224
	s_and_b32 s0, s3, 0x7fffff00
	s_lshl_b32 s9, s1, 2
	v_readlane_b32 s14, v252, 20
	v_lshlrev_b32_e32 v0, 4, v33
	v_ashrrev_i32_e32 v34, 4, v33
	v_add_u32_e32 v4, 0x200, v33
	s_add_u32 s14, s14, s9
	v_readlane_b32 s9, v252, 21
	v_and_b32_e32 v192, 0xf0, v0
	v_add_u32_e32 v0, s0, v34
	v_ashrrev_i32_e32 v36, 4, v4
	v_add_u32_e32 v8, 0x400, v33
	s_addc_u32 s15, s9, 0
	s_waitcnt lgkmcnt(0)
	v_ashrrev_i32_e32 v1, 31, v0
	v_add_u32_e32 v4, s0, v36
	v_ashrrev_i32_e32 v37, 4, v8
	v_add_u32_e32 v12, 0x600, v33
	v_lshl_add_u64 v[28:29], s[14:15], 0, v[192:193]
	v_lshlrev_b64 v[0:1], 15, v[0:1]
	v_ashrrev_i32_e32 v5, 31, v4
	v_add_u32_e32 v8, s0, v37
	v_ashrrev_i32_e32 v38, 4, v12
	v_add_u32_e32 v16, 0x800, v33
	v_lshl_add_u64 v[0:1], v[28:29], 0, v[0:1]
	v_lshlrev_b64 v[4:5], 15, v[4:5]
	v_ashrrev_i32_e32 v9, 31, v8
	v_add_u32_e32 v12, s0, v38
	v_ashrrev_i32_e32 v39, 4, v16
	v_add_u32_e32 v20, 0xa00, v33
	global_load_dwordx4 v[0:3], v[0:1], off nt
	v_lshl_add_u64 v[4:5], v[28:29], 0, v[4:5]
	v_lshlrev_b64 v[8:9], 15, v[8:9]
	v_ashrrev_i32_e32 v13, 31, v12
	v_add_u32_e32 v16, s0, v39
	v_ashrrev_i32_e32 v40, 4, v20
	v_add_u32_e32 v24, 0xc00, v33
	global_load_dwordx4 v[4:7], v[4:5], off nt
	v_lshl_add_u64 v[8:9], v[28:29], 0, v[8:9]
	v_lshlrev_b64 v[12:13], 15, v[12:13]
	v_ashrrev_i32_e32 v17, 31, v16
	v_add_u32_e32 v20, s0, v40
	v_ashrrev_i32_e32 v41, 4, v24
	v_add_u32_e32 v30, 0xe00, v33
	global_load_dwordx4 v[8:11], v[8:9], off nt
	v_lshl_add_u64 v[12:13], v[28:29], 0, v[12:13]
	v_lshlrev_b64 v[16:17], 15, v[16:17]
	v_ashrrev_i32_e32 v21, 31, v20
	v_add_u32_e32 v24, s0, v41
	v_ashrrev_i32_e32 v42, 4, v30
	global_load_dwordx4 v[12:15], v[12:13], off nt
	v_lshl_add_u64 v[16:17], v[28:29], 0, v[16:17]
	v_lshlrev_b64 v[20:21], 15, v[20:21]
	v_ashrrev_i32_e32 v25, 31, v24
	v_add_u32_e32 v30, s0, v42
	global_load_dwordx4 v[16:19], v[16:17], off nt
	v_lshl_add_u64 v[20:21], v[28:29], 0, v[20:21]
	v_lshlrev_b64 v[24:25], 15, v[24:25]
	v_ashrrev_i32_e32 v31, 31, v30
	global_load_dwordx4 v[20:23], v[20:21], off nt
	v_lshl_add_u64 v[24:25], v[28:29], 0, v[24:25]
	v_lshlrev_b64 v[30:31], 15, v[30:31]
	global_load_dwordx4 v[24:27], v[24:25], off nt
	v_lshl_add_u64 v[28:29], v[28:29], 0, v[30:31]
	global_load_dwordx4 v[28:31], v[28:29], off nt
	v_add_u32_e32 v32, 0, v192
	v_mad_u64_u32 v[34:35], s[14:15], v34, s97, v[32:33]
	s_lshl_b32 s64, s0, 1
	s_waitcnt vmcnt(0)
	ds_write2_b32 v34, v0, v1 offset1:1
	ds_write2_b32 v34, v2, v3 offset0:2 offset1:3
	v_mad_u64_u32 v[0:1], s[14:15], v36, s97, v[32:33]
	ds_write2_b32 v0, v4, v5 offset1:1
	ds_write2_b32 v0, v6, v7 offset0:2 offset1:3
	v_mad_u64_u32 v[0:1], s[14:15], v37, s97, v[32:33]
	ds_write2_b32 v0, v8, v9 offset1:1
	ds_write2_b32 v0, v10, v11 offset0:2 offset1:3
	v_mad_u64_u32 v[0:1], s[14:15], v38, s97, v[32:33]
	ds_write2_b32 v0, v12, v13 offset1:1
	ds_write2_b32 v0, v14, v15 offset0:2 offset1:3
	v_mad_u64_u32 v[0:1], s[14:15], v39, s97, v[32:33]
	ds_write2_b32 v0, v16, v17 offset1:1
	ds_write2_b32 v0, v18, v19 offset0:2 offset1:3
	v_mad_u64_u32 v[0:1], s[14:15], v40, s97, v[32:33]
	ds_write2_b32 v0, v20, v21 offset1:1
	ds_write2_b32 v0, v22, v23 offset0:2 offset1:3
	v_mad_u64_u32 v[0:1], s[14:15], v41, s97, v[32:33]
	ds_write2_b32 v0, v24, v25 offset1:1
	ds_write2_b32 v0, v26, v27 offset0:2 offset1:3
	v_mad_u64_u32 v[0:1], s[14:15], v42, s97, v[32:33]
	v_ashrrev_i32_e32 v2, 3, v33
	ds_write2_b32 v0, v28, v29 offset1:1
	ds_write2_b32 v0, v30, v31 offset0:2 offset1:3
	v_add_u32_e32 v0, s1, v2
	v_lshlrev_b32_e32 v3, 3, v33
	v_ashrrev_i32_e32 v1, 31, v0
	v_and_b32_e32 v3, 56, v3
	v_readlane_b32 s14, v252, 22
	v_lshlrev_b32_e32 v2, 2, v2
	v_mul_u32_u24_e32 v4, 0x104, v3
	v_lshlrev_b64 v[0:1], 12, v[0:1]
	v_readlane_b32 s15, v252, 23
	v_add3_u32 v32, 0, v2, v4
	v_lshlrev_b32_e32 v192, 1, v3
	v_lshl_add_u64 v[0:1], s[14:15], 0, v[0:1]
	v_lshl_add_u64 v[0:1], v[0:1], 0, s[64:65]
	v_add_u32_e32 v8, 0x400, v32
	s_waitcnt lgkmcnt(0)
	s_barrier
	v_lshl_add_u64 v[4:5], v[0:1], 0, v[192:193]
	ds_read2_b32 v[0:1], v32 offset1:65
	ds_read2_b32 v[2:3], v32 offset0:130 offset1:195
	ds_read2_b32 v[6:7], v8 offset0:4 offset1:69
	ds_read2_b32 v[8:9], v8 offset0:134 offset1:199
	v_add_u32_e32 v10, 0x4000, v32
	v_add_u32_e32 v12, 0x4200, v32
	v_add_u32_e32 v14, 0x4400, v32
	v_add_u32_e32 v16, 0x4600, v32
	v_add_u32_e32 v18, 0x8000, v32
	v_add_u32_e32 v22, 0x8400, v32
	ds_read2_b32 v[10:11], v10 offset0:64 offset1:129
	ds_read2_b32 v[12:13], v12 offset0:66 offset1:131
	ds_read2_b32 v[14:15], v14 offset0:68 offset1:133
	ds_read2_b32 v[16:17], v16 offset0:70 offset1:135
	ds_read2_b32 v[18:19], v18 offset0:128 offset1:193
	ds_read2_b32 v[20:21], v22 offset0:2 offset1:67
	ds_read2_b32 v[22:23], v22 offset0:132 offset1:197
	v_add_u32_e32 v24, 0x8800, v32
	v_add_u32_e32 v26, 0xc200, v32
	v_add_u32_e32 v28, 0xc400, v32
	v_add_u32_e32 v30, 0xc600, v32
	v_add_u32_e32 v32, 0xc800, v32
	ds_read2_b32 v[24:25], v24 offset0:6 offset1:71
	ds_read2_b32 v[26:27], v26 offset0:64 offset1:129
	ds_read2_b32 v[28:29], v28 offset0:66 offset1:131
	ds_read2_b32 v[30:31], v30 offset0:68 offset1:133
	ds_read2_b32 v[32:33], v32 offset0:70 offset1:135
	s_waitcnt lgkmcnt(14)
	v_cvt_pk_bf16_f32 v0, v0, v1
	v_cvt_pk_bf16_f32 v1, v2, v3
	s_waitcnt lgkmcnt(13)
	v_cvt_pk_bf16_f32 v2, v6, v7
	s_waitcnt lgkmcnt(12)
	v_cvt_pk_bf16_f32 v3, v8, v9
	global_store_dwordx4 v[4:5], v[0:3], off nt
	s_waitcnt lgkmcnt(11)
	s_nop 0
	v_cvt_pk_bf16_f32 v0, v10, v11
	s_waitcnt lgkmcnt(10)
	v_cvt_pk_bf16_f32 v1, v12, v13
	s_waitcnt lgkmcnt(9)
	v_cvt_pk_bf16_f32 v2, v14, v15
	s_waitcnt lgkmcnt(8)
	v_cvt_pk_bf16_f32 v3, v16, v17
	global_store_dwordx4 v[4:5], v[0:3], off offset:128 nt
	s_waitcnt lgkmcnt(7)
	s_nop 0
	v_cvt_pk_bf16_f32 v0, v18, v19
	s_waitcnt lgkmcnt(6)
	v_cvt_pk_bf16_f32 v1, v20, v21
	s_waitcnt lgkmcnt(5)
	v_cvt_pk_bf16_f32 v2, v22, v23
	s_waitcnt lgkmcnt(4)
	v_cvt_pk_bf16_f32 v3, v24, v25
	global_store_dwordx4 v[4:5], v[0:3], off offset:256 nt
	s_waitcnt lgkmcnt(3)
	s_nop 0
	v_cvt_pk_bf16_f32 v0, v26, v27
	s_waitcnt lgkmcnt(2)
	v_cvt_pk_bf16_f32 v1, v28, v29
	s_waitcnt lgkmcnt(1)
	v_cvt_pk_bf16_f32 v2, v30, v31
	s_waitcnt lgkmcnt(0)
	v_cvt_pk_bf16_f32 v3, v32, v33
	global_store_dwordx4 v[4:5], v[0:3], off offset:384 nt
	s_barrier
	s_branch .LBB0_285

.LBB0_546:
	s_and_b32 s0, s3, 0xffffff00
	s_and_b32 s1, s2, 0x7c0
	v_mov_b32_e32 v33, v224
	s_addk_i32 s0, 0xe000
	s_lshl_b32 s5, s1, 2
	v_lshlrev_b32_e32 v0, 4, v33
	v_ashrrev_i32_e32 v34, 4, v33
	v_add_u32_e32 v4, 0x200, v33
	s_add_u32 s10, s55, s5
	v_and_b32_e32 v192, 0xf0, v0
	v_add_u32_e32 v0, s0, v34
	v_ashrrev_i32_e32 v36, 4, v4
	v_add_u32_e32 v8, 0x400, v33
	s_addc_u32 s11, s58, 0
	v_ashrrev_i32_e32 v1, 31, v0
	v_add_u32_e32 v4, s0, v36
	v_ashrrev_i32_e32 v37, 4, v8
	v_add_u32_e32 v12, 0x600, v33
	v_lshl_add_u64 v[28:29], s[10:11], 0, v[192:193]
	v_lshlrev_b64 v[0:1], 13, v[0:1]
	v_ashrrev_i32_e32 v5, 31, v4
	v_add_u32_e32 v8, s0, v37
	v_ashrrev_i32_e32 v38, 4, v12
	v_add_u32_e32 v16, 0x800, v33
	v_lshl_add_u64 v[0:1], v[28:29], 0, v[0:1]
	v_lshlrev_b64 v[4:5], 13, v[4:5]
	v_ashrrev_i32_e32 v9, 31, v8
	v_add_u32_e32 v12, s0, v38
	v_ashrrev_i32_e32 v39, 4, v16
	v_add_u32_e32 v20, 0xa00, v33
	global_load_dwordx4 v[0:3], v[0:1], off nt
	v_lshl_add_u64 v[4:5], v[28:29], 0, v[4:5]
	v_lshlrev_b64 v[8:9], 13, v[8:9]
	v_ashrrev_i32_e32 v13, 31, v12
	v_add_u32_e32 v16, s0, v39
	v_ashrrev_i32_e32 v40, 4, v20
	v_add_u32_e32 v24, 0xc00, v33
	global_load_dwordx4 v[4:7], v[4:5], off nt
	v_lshl_add_u64 v[8:9], v[28:29], 0, v[8:9]
	v_lshlrev_b64 v[12:13], 13, v[12:13]
	v_ashrrev_i32_e32 v17, 31, v16
	v_add_u32_e32 v20, s0, v40
	v_ashrrev_i32_e32 v41, 4, v24
	v_add_u32_e32 v30, 0xe00, v33
	global_load_dwordx4 v[8:11], v[8:9], off nt
	v_lshl_add_u64 v[12:13], v[28:29], 0, v[12:13]
	v_lshlrev_b64 v[16:17], 13, v[16:17]
	v_ashrrev_i32_e32 v21, 31, v20
	v_add_u32_e32 v24, s0, v41
	v_ashrrev_i32_e32 v42, 4, v30
	global_load_dwordx4 v[12:15], v[12:13], off nt
	v_lshl_add_u64 v[16:17], v[28:29], 0, v[16:17]
	v_lshlrev_b64 v[20:21], 13, v[20:21]
	v_ashrrev_i32_e32 v25, 31, v24
	v_add_u32_e32 v30, s0, v42
	global_load_dwordx4 v[16:19], v[16:17], off nt
	v_lshl_add_u64 v[20:21], v[28:29], 0, v[20:21]
	v_lshlrev_b64 v[24:25], 13, v[24:25]
	v_ashrrev_i32_e32 v31, 31, v30
	global_load_dwordx4 v[20:23], v[20:21], off nt
	v_lshl_add_u64 v[24:25], v[28:29], 0, v[24:25]
	v_lshlrev_b64 v[30:31], 13, v[30:31]
	global_load_dwordx4 v[24:27], v[24:25], off nt
	v_lshl_add_u64 v[28:29], v[28:29], 0, v[30:31]
	global_load_dwordx4 v[28:31], v[28:29], off nt
	v_add_u32_e32 v32, 0, v192
	v_mad_u64_u32 v[34:35], s[10:11], v34, s97, v[32:33]
	s_add_i32 s4, s4, 48
	s_addk_i32 s3, 0x180
	s_addk_i32 s2, 0xc00
	s_waitcnt vmcnt(0)
	ds_write2_b32 v34, v0, v1 offset1:1
	ds_write2_b32 v34, v2, v3 offset0:2 offset1:3
	v_mad_u64_u32 v[0:1], s[10:11], v36, s97, v[32:33]
	ds_write2_b32 v0, v4, v5 offset1:1
	ds_write2_b32 v0, v6, v7 offset0:2 offset1:3
	v_mad_u64_u32 v[0:1], s[10:11], v37, s97, v[32:33]
	ds_write2_b32 v0, v8, v9 offset1:1
	ds_write2_b32 v0, v10, v11 offset0:2 offset1:3
	v_mad_u64_u32 v[0:1], s[10:11], v38, s97, v[32:33]
	ds_write2_b32 v0, v12, v13 offset1:1
	ds_write2_b32 v0, v14, v15 offset0:2 offset1:3
	v_mad_u64_u32 v[0:1], s[10:11], v39, s97, v[32:33]
	ds_write2_b32 v0, v16, v17 offset1:1
	ds_write2_b32 v0, v18, v19 offset0:2 offset1:3
	v_mad_u64_u32 v[0:1], s[10:11], v40, s97, v[32:33]
	ds_write2_b32 v0, v20, v21 offset1:1
	ds_write2_b32 v0, v22, v23 offset0:2 offset1:3
	v_mad_u64_u32 v[0:1], s[10:11], v41, s97, v[32:33]
	ds_write2_b32 v0, v24, v25 offset1:1
	ds_write2_b32 v0, v26, v27 offset0:2 offset1:3
	v_mad_u64_u32 v[0:1], s[10:11], v42, s97, v[32:33]
	v_ashrrev_i32_e32 v2, 3, v33
	ds_write2_b32 v0, v28, v29 offset1:1
	ds_write2_b32 v0, v30, v31 offset0:2 offset1:3
	v_add_u32_e32 v0, s1, v2
	v_lshlrev_b32_e32 v3, 3, v33
	v_ashrrev_i32_e32 v1, 31, v0
	v_and_b32_e32 v3, 56, v3
	v_lshlrev_b32_e32 v2, 2, v2
	v_mul_u32_u24_e32 v4, 0x104, v3
	v_lshlrev_b64 v[0:1], 14, v[0:1]
	s_ashr_i32 s1, s0, 31
	v_add3_u32 v32, 0, v2, v4
	v_lshl_add_u64 v[0:1], s[62:63], 0, v[0:1]
	v_lshl_add_u64 v[0:1], s[0:1], 1, v[0:1]
	v_lshlrev_b32_e32 v192, 1, v3
	v_add_u32_e32 v8, 0x400, v32
	s_waitcnt lgkmcnt(0)
	s_barrier
	v_lshl_add_u64 v[4:5], v[0:1], 0, v[192:193]
	ds_read2_b32 v[0:1], v32 offset1:65
	ds_read2_b32 v[2:3], v32 offset0:130 offset1:195
	ds_read2_b32 v[6:7], v8 offset0:4 offset1:69
	ds_read2_b32 v[8:9], v8 offset0:134 offset1:199
	v_add_u32_e32 v10, 0x4000, v32
	v_add_u32_e32 v12, 0x4200, v32
	v_add_u32_e32 v14, 0x4400, v32
	v_add_u32_e32 v16, 0x4600, v32
	v_add_u32_e32 v18, 0x8000, v32
	v_add_u32_e32 v22, 0x8400, v32
	ds_read2_b32 v[10:11], v10 offset0:64 offset1:129
	ds_read2_b32 v[12:13], v12 offset0:66 offset1:131
	ds_read2_b32 v[14:15], v14 offset0:68 offset1:133
	ds_read2_b32 v[16:17], v16 offset0:70 offset1:135
	ds_read2_b32 v[18:19], v18 offset0:128 offset1:193
	ds_read2_b32 v[20:21], v22 offset0:2 offset1:67
	ds_read2_b32 v[22:23], v22 offset0:132 offset1:197
	v_add_u32_e32 v24, 0x8800, v32
	v_add_u32_e32 v26, 0xc200, v32
	v_add_u32_e32 v28, 0xc400, v32
	v_add_u32_e32 v30, 0xc600, v32
	v_add_u32_e32 v32, 0xc800, v32
	ds_read2_b32 v[24:25], v24 offset0:6 offset1:71
	ds_read2_b32 v[26:27], v26 offset0:64 offset1:129
	ds_read2_b32 v[28:29], v28 offset0:66 offset1:131
	ds_read2_b32 v[30:31], v30 offset0:68 offset1:133
	ds_read2_b32 v[32:33], v32 offset0:70 offset1:135
	s_waitcnt lgkmcnt(14)
	v_cvt_pk_bf16_f32 v0, v0, v1
	v_cvt_pk_bf16_f32 v1, v2, v3
	s_waitcnt lgkmcnt(13)
	v_cvt_pk_bf16_f32 v2, v6, v7
	s_waitcnt lgkmcnt(12)
	v_cvt_pk_bf16_f32 v3, v8, v9
	global_store_dwordx4 v[4:5], v[0:3], off nt
	s_cmpk_gt_i32 s4, 0x7cf
	s_waitcnt lgkmcnt(11)
	v_cvt_pk_bf16_f32 v0, v10, v11
	s_waitcnt lgkmcnt(10)
	v_cvt_pk_bf16_f32 v1, v12, v13
	s_waitcnt lgkmcnt(9)
	v_cvt_pk_bf16_f32 v2, v14, v15
	s_waitcnt lgkmcnt(8)
	v_cvt_pk_bf16_f32 v3, v16, v17
	global_store_dwordx4 v[4:5], v[0:3], off offset:128 nt
	s_waitcnt lgkmcnt(7)
	s_nop 0
	v_cvt_pk_bf16_f32 v0, v18, v19
	s_waitcnt lgkmcnt(6)
	v_cvt_pk_bf16_f32 v1, v20, v21
	s_waitcnt lgkmcnt(5)
	v_cvt_pk_bf16_f32 v2, v22, v23
	s_waitcnt lgkmcnt(4)
	v_cvt_pk_bf16_f32 v3, v24, v25
	global_store_dwordx4 v[4:5], v[0:3], off offset:256 nt
	s_waitcnt lgkmcnt(3)
	s_nop 0
	v_cvt_pk_bf16_f32 v0, v26, v27
	s_waitcnt lgkmcnt(2)
	v_cvt_pk_bf16_f32 v1, v28, v29
	s_waitcnt lgkmcnt(1)
	v_cvt_pk_bf16_f32 v2, v30, v31
	s_waitcnt lgkmcnt(0)
	v_cvt_pk_bf16_f32 v3, v32, v33
	global_store_dwordx4 v[4:5], v[0:3], off offset:384 nt
	s_barrier
	s_cbranch_scc0 .LBB0_546

.LBB0_613:
	s_andn2_b64 vcc, exec, s[2:3]
	s_cbranch_vccnz .LBB0_639
	s_add_i32 s2, s67, 0xfffffd00
	s_add_i32 s3, s67, 0xfffff200
	s_cmpk_lt_u32 s2, 0xb00
	s_cselect_b32 s28, s2, s3
	s_cmpk_lt_u32 s3, 0xb00
	s_cselect_b64 s[4:5], -1, 0
	s_add_i32 s3, s28, 0xfffffd00
	s_cmp_lt_u32 s3, 0xffffff00
	s_cselect_b64 s[14:15], -1, 0
	s_and_b64 s[4:5], s[4:5], s[14:15]
	s_and_b64 vcc, exec, s[4:5]
	s_cbranch_vccnz .LBB0_639
	s_cmpk_gt_u32 s2, 0xaff
	s_cselect_b64 s[14:15], -1, 0
	s_cmpk_gt_u32 s28, 0x1ff
	s_mov_b64 s[2:3], -1
	s_cbranch_scc0 .LBB0_629
	s_cmpk_gt_u32 s28, 0x2ff
	s_cbranch_scc0 .LBB0_622
	s_and_b64 s[2:3], s[14:15], exec
	s_cselect_b32 s35, 0x4000000, 0
	s_lshl_b32 s29, s28, 6
	s_and_b64 s[2:3], s[14:15], exec
	s_cselect_b32 s34, 0x2000000, 0
	s_cmpk_gt_u32 s28, 0x6ff
	s_mov_b64 s[2:3], -1
	s_cbranch_scc0 .LBB0_619
	s_add_u32 s3, s22, s35
	s_addc_u32 s47, s23, 0
	s_lshl_b32 s2, s28, 3
	s_and_b32 s2, s2, 0x7f00
	s_addk_i32 s2, 0xc800
	s_and_b32 s64, s29, 0x7c0
	v_readlane_b32 s4, v251, 63
	v_mov_b32_e32 v33, v224
	s_add_u32 s4, s4, s34
	v_readlane_b32 s5, v252, 0
	s_addc_u32 s5, s5, 0
	v_add_u32_e32 v2, 0x200, v33
	v_add_u32_e32 v8, 0x400, v33
	v_add_u32_e32 v10, 0x600, v33
	s_lshl_b32 s46, s64, 2
	v_lshlrev_b32_e32 v0, 4, v33
	v_ashrrev_i32_e32 v34, 4, v33
	v_ashrrev_i32_e32 v36, 4, v2
	v_ashrrev_i32_e32 v38, 4, v8
	v_ashrrev_i32_e32 v40, 4, v10
	v_add_u32_e32 v16, 0x800, v33
	v_add_u32_e32 v18, 0xa00, v33
	s_add_u32 s46, s3, s46
	v_and_b32_e32 v192, 0xf0, v0
	v_add_u32_e32 v0, s2, v34
	v_add_u32_e32 v2, s2, v36
	v_add_u32_e32 v8, s2, v38
	v_add_u32_e32 v10, s2, v40
	v_ashrrev_i32_e32 v42, 4, v16
	v_ashrrev_i32_e32 v69, 4, v18
	v_add_u32_e32 v24, 0xc00, v33
	s_addc_u32 s47, s47, 0
	s_waitcnt lgkmcnt(0)
	v_ashrrev_i32_e32 v1, 31, v0
	v_ashrrev_i32_e32 v3, 31, v2
	v_ashrrev_i32_e32 v9, 31, v8
	v_ashrrev_i32_e32 v11, 31, v10
	v_add_u32_e32 v16, s2, v42
	v_add_u32_e32 v18, s2, v69
	v_ashrrev_i32_e32 v79, 4, v24
	v_add_u32_e32 v30, 0xe00, v33
	v_lshl_add_u64 v[28:29], s[46:47], 0, v[192:193]
	v_lshlrev_b64 v[0:1], 13, v[0:1]
	v_lshlrev_b64 v[2:3], 13, v[2:3]
	v_lshlrev_b64 v[8:9], 13, v[8:9]
	v_lshlrev_b64 v[10:11], 13, v[10:11]
	v_ashrrev_i32_e32 v17, 31, v16
	v_ashrrev_i32_e32 v19, 31, v18
	v_add_u32_e32 v24, s2, v79
	v_ashrrev_i32_e32 v80, 4, v30
	v_lshl_add_u64 v[0:1], v[28:29], 0, v[0:1]
	v_lshl_add_u64 v[4:5], v[28:29], 0, v[2:3]
	v_lshl_add_u64 v[8:9], v[28:29], 0, v[8:9]
	v_lshl_add_u64 v[12:13], v[28:29], 0, v[10:11]
	v_lshlrev_b64 v[16:17], 13, v[16:17]
	v_lshlrev_b64 v[18:19], 13, v[18:19]
	v_ashrrev_i32_e32 v25, 31, v24
	v_add_u32_e32 v30, s2, v80
	global_load_dwordx4 v[0:3], v[0:1], off nt
	s_nop 0
	global_load_dwordx4 v[4:7], v[4:5], off nt
	s_nop 0
	global_load_dwordx4 v[8:11], v[8:9], off nt
	s_nop 0
	global_load_dwordx4 v[12:15], v[12:13], off nt
	v_lshl_add_u64 v[16:17], v[28:29], 0, v[16:17]
	v_lshl_add_u64 v[20:21], v[28:29], 0, v[18:19]
	v_lshlrev_b64 v[24:25], 13, v[24:25]
	v_ashrrev_i32_e32 v31, 31, v30
	global_load_dwordx4 v[16:19], v[16:17], off nt
	s_nop 0
	global_load_dwordx4 v[20:23], v[20:21], off nt
	v_lshl_add_u64 v[24:25], v[28:29], 0, v[24:25]
	v_lshlrev_b64 v[30:31], 13, v[30:31]
	global_load_dwordx4 v[24:27], v[24:25], off nt
	v_lshl_add_u64 v[28:29], v[28:29], 0, v[30:31]
	global_load_dwordx4 v[28:31], v[28:29], off nt
	v_add_u32_e32 v32, 0, v192
	v_mad_u64_u32 v[34:35], s[46:47], v34, s97, v[32:33]
	v_mad_u64_u32 v[36:37], s[46:47], v36, s97, v[32:33]
	v_mad_u64_u32 v[38:39], s[46:47], v38, s97, v[32:33]
	v_mad_u64_u32 v[40:41], s[46:47], v40, s97, v[32:33]
	v_mad_u64_u32 v[42:43], s[46:47], v42, s97, v[32:33]
	s_ashr_i32 s3, s2, 31
	s_mov_b32 s9, 0xc000
	s_waitcnt vmcnt(0)
	ds_write2_b32 v34, v0, v1 offset1:1
	ds_write2_b32 v34, v2, v3 offset0:2 offset1:3
	ds_write2_b32 v36, v4, v5 offset1:1
	ds_write2_b32 v36, v6, v7 offset0:2 offset1:3
	ds_write2_b32 v38, v8, v9 offset1:1
	ds_write2_b32 v38, v10, v11 offset0:2 offset1:3
	ds_write2_b32 v40, v12, v13 offset1:1
	ds_write2_b32 v40, v14, v15 offset0:2 offset1:3
	ds_write2_b32 v42, v16, v17 offset1:1
	ds_write2_b32 v42, v18, v19 offset0:2 offset1:3
	v_mad_u64_u32 v[0:1], s[46:47], v69, s97, v[32:33]
	ds_write2_b32 v0, v20, v21 offset1:1
	ds_write2_b32 v0, v22, v23 offset0:2 offset1:3
	v_mad_u64_u32 v[0:1], s[46:47], v79, s97, v[32:33]
	ds_write2_b32 v0, v24, v25 offset1:1
	ds_write2_b32 v0, v26, v27 offset0:2 offset1:3
	v_mad_u64_u32 v[0:1], s[46:47], v80, s97, v[32:33]
	v_ashrrev_i32_e32 v2, 3, v33
	ds_write2_b32 v0, v28, v29 offset1:1
	ds_write2_b32 v0, v30, v31 offset0:2 offset1:3
	v_add_u32_e32 v0, s64, v2
	v_lshlrev_b32_e32 v3, 3, v33
	v_ashrrev_i32_e32 v1, 31, v0
	v_and_b32_e32 v3, 56, v3
	v_lshlrev_b32_e32 v2, 2, v2
	v_mul_u32_u24_e32 v4, 0x104, v3
	v_lshlrev_b64 v[0:1], 14, v[0:1]
	v_add3_u32 v32, 0, v2, v4
	v_lshl_add_u64 v[0:1], s[4:5], 0, v[0:1]
	v_lshl_add_u64 v[0:1], s[2:3], 1, v[0:1]
	v_lshlrev_b32_e32 v192, 1, v3
	v_add_u32_e32 v8, 0x400, v32
	s_waitcnt lgkmcnt(0)
	s_barrier
	v_lshl_add_u64 v[4:5], v[0:1], 0, v[192:193]
	ds_read2_b32 v[0:1], v32 offset1:65
	ds_read2_b32 v[2:3], v32 offset0:130 offset1:195
	ds_read2_b32 v[6:7], v8 offset0:4 offset1:69
	ds_read2_b32 v[8:9], v8 offset0:134 offset1:199
	v_add_u32_e32 v10, 0x4000, v32
	v_add_u32_e32 v12, 0x4200, v32
	v_add_u32_e32 v14, 0x4400, v32
	v_add_u32_e32 v16, 0x4600, v32
	v_add_u32_e32 v18, 0x8000, v32
	v_add_u32_e32 v22, 0x8400, v32
	ds_read2_b32 v[10:11], v10 offset0:64 offset1:129
	ds_read2_b32 v[12:13], v12 offset0:66 offset1:131
	ds_read2_b32 v[14:15], v14 offset0:68 offset1:133
	ds_read2_b32 v[16:17], v16 offset0:70 offset1:135
	ds_read2_b32 v[18:19], v18 offset0:128 offset1:193
	ds_read2_b32 v[20:21], v22 offset0:2 offset1:67
	ds_read2_b32 v[22:23], v22 offset0:132 offset1:197
	v_add_u32_e32 v24, 0x8800, v32
	v_add_u32_e32 v26, 0xc200, v32
	v_add_u32_e32 v28, 0xc400, v32
	v_add_u32_e32 v30, 0xc600, v32
	v_add_u32_e32 v32, 0xc800, v32
	ds_read2_b32 v[24:25], v24 offset0:6 offset1:71
	ds_read2_b32 v[26:27], v26 offset0:64 offset1:129
	ds_read2_b32 v[28:29], v28 offset0:66 offset1:131
	ds_read2_b32 v[30:31], v30 offset0:68 offset1:133
	ds_read2_b32 v[32:33], v32 offset0:70 offset1:135
	s_waitcnt lgkmcnt(14)
	v_cvt_pk_bf16_f32 v0, v0, v1
	v_cvt_pk_bf16_f32 v1, v2, v3
	s_waitcnt lgkmcnt(13)
	v_cvt_pk_bf16_f32 v2, v6, v7
	s_waitcnt lgkmcnt(12)
	v_cvt_pk_bf16_f32 v3, v8, v9
	global_store_dwordx4 v[4:5], v[0:3], off nt
	s_mov_b64 s[2:3], 0
	s_waitcnt lgkmcnt(11)
	v_cvt_pk_bf16_f32 v0, v10, v11
	s_waitcnt lgkmcnt(10)
	v_cvt_pk_bf16_f32 v1, v12, v13
	s_waitcnt lgkmcnt(9)
	v_cvt_pk_bf16_f32 v2, v14, v15
	s_waitcnt lgkmcnt(8)
	v_cvt_pk_bf16_f32 v3, v16, v17
	global_store_dwordx4 v[4:5], v[0:3], off offset:128 nt
	s_waitcnt lgkmcnt(7)
	s_nop 0
	v_cvt_pk_bf16_f32 v0, v18, v19
	s_waitcnt lgkmcnt(6)
	v_cvt_pk_bf16_f32 v1, v20, v21
	s_waitcnt lgkmcnt(5)
	v_cvt_pk_bf16_f32 v2, v22, v23
	s_waitcnt lgkmcnt(4)
	v_cvt_pk_bf16_f32 v3, v24, v25
	global_store_dwordx4 v[4:5], v[0:3], off offset:256 nt
	s_waitcnt lgkmcnt(3)
	s_nop 0
	v_cvt_pk_bf16_f32 v0, v26, v27
	s_waitcnt lgkmcnt(2)
	v_cvt_pk_bf16_f32 v1, v28, v29
	s_waitcnt lgkmcnt(1)
	v_cvt_pk_bf16_f32 v2, v30, v31
	s_waitcnt lgkmcnt(0)
	v_cvt_pk_bf16_f32 v3, v32, v33
	global_store_dwordx4 v[4:5], v[0:3], off offset:384 nt
	s_barrier
.LBB0_619:
	s_andn2_b64 vcc, exec, s[2:3]
	s_cbranch_vccnz .LBB0_621
	s_add_u32 s4, s20, s35
	s_addc_u32 s5, s21, 0
	s_lshl_b32 s2, s28, 1
	s_and_b32 s2, s2, 0xf00
	s_add_i32 s64, s2, 0xfffffa00
	s_and_b32 s29, s29, 0x1fc0
	v_readlane_b32 s2, v252, 1
	v_mov_b32_e32 v33, v224
	s_add_u32 s2, s2, s34
	v_readlane_b32 s3, v252, 2
	s_addc_u32 s3, s3, 0
	v_add_u32_e32 v2, 0x200, v33
	v_add_u32_e32 v8, 0x400, v33
	v_add_u32_e32 v10, 0x600, v33
	s_lshl_b32 s34, s29, 2
	v_lshlrev_b32_e32 v0, 4, v33
	v_ashrrev_i32_e32 v34, 4, v33
	v_ashrrev_i32_e32 v36, 4, v2
	v_ashrrev_i32_e32 v38, 4, v8
	v_ashrrev_i32_e32 v40, 4, v10
	v_add_u32_e32 v16, 0x800, v33
	v_add_u32_e32 v18, 0xa00, v33
	s_add_u32 s4, s4, s34
	v_and_b32_e32 v192, 0xf0, v0
	v_add_u32_e32 v0, s64, v34
	v_add_u32_e32 v2, s64, v36
	v_add_u32_e32 v8, s64, v38
	v_add_u32_e32 v10, s64, v40
	v_ashrrev_i32_e32 v42, 4, v16
	v_ashrrev_i32_e32 v69, 4, v18
	v_add_u32_e32 v24, 0xc00, v33
	s_addc_u32 s5, s5, 0
	s_waitcnt lgkmcnt(0)
	v_ashrrev_i32_e32 v1, 31, v0
	v_ashrrev_i32_e32 v3, 31, v2
	v_ashrrev_i32_e32 v9, 31, v8
	v_ashrrev_i32_e32 v11, 31, v10
	v_add_u32_e32 v16, s64, v42
	v_add_u32_e32 v18, s64, v69
	v_ashrrev_i32_e32 v79, 4, v24
	v_add_u32_e32 v30, 0xe00, v33
	v_lshl_add_u64 v[28:29], s[4:5], 0, v[192:193]
	v_lshlrev_b64 v[0:1], 15, v[0:1]
	v_lshlrev_b64 v[2:3], 15, v[2:3]
	v_lshlrev_b64 v[8:9], 15, v[8:9]
	v_lshlrev_b64 v[10:11], 15, v[10:11]
	v_ashrrev_i32_e32 v17, 31, v16
	v_ashrrev_i32_e32 v19, 31, v18
	v_add_u32_e32 v24, s64, v79
	v_ashrrev_i32_e32 v80, 4, v30
	v_lshl_add_u64 v[0:1], v[28:29], 0, v[0:1]
	v_lshl_add_u64 v[4:5], v[28:29], 0, v[2:3]
	v_lshl_add_u64 v[8:9], v[28:29], 0, v[8:9]
	v_lshl_add_u64 v[12:13], v[28:29], 0, v[10:11]
	v_lshlrev_b64 v[16:17], 15, v[16:17]
	v_lshlrev_b64 v[18:19], 15, v[18:19]
	v_ashrrev_i32_e32 v25, 31, v24
	v_add_u32_e32 v30, s64, v80
	global_load_dwordx4 v[0:3], v[0:1], off nt
	s_nop 0
	global_load_dwordx4 v[4:7], v[4:5], off nt
	s_nop 0
	global_load_dwordx4 v[8:11], v[8:9], off nt
	s_nop 0
	global_load_dwordx4 v[12:15], v[12:13], off nt
	v_lshl_add_u64 v[16:17], v[28:29], 0, v[16:17]
	v_lshl_add_u64 v[20:21], v[28:29], 0, v[18:19]
	v_lshlrev_b64 v[24:25], 15, v[24:25]
	v_ashrrev_i32_e32 v31, 31, v30
	global_load_dwordx4 v[16:19], v[16:17], off nt
	s_nop 0
	global_load_dwordx4 v[20:23], v[20:21], off nt
	v_lshl_add_u64 v[24:25], v[28:29], 0, v[24:25]
	v_lshlrev_b64 v[30:31], 15, v[30:31]
	global_load_dwordx4 v[24:27], v[24:25], off nt
	v_lshl_add_u64 v[28:29], v[28:29], 0, v[30:31]
	global_load_dwordx4 v[28:31], v[28:29], off nt
	v_add_u32_e32 v32, 0, v192
	v_mad_u64_u32 v[34:35], s[4:5], v34, s97, v[32:33]
	v_mad_u64_u32 v[36:37], s[4:5], v36, s97, v[32:33]
	v_mad_u64_u32 v[38:39], s[4:5], v38, s97, v[32:33]
	v_mad_u64_u32 v[40:41], s[4:5], v40, s97, v[32:33]
	v_mad_u64_u32 v[42:43], s[4:5], v42, s97, v[32:33]
	s_waitcnt vmcnt(0)
	ds_write2_b32 v34, v0, v1 offset1:1
	ds_write2_b32 v34, v2, v3 offset0:2 offset1:3
	ds_write2_b32 v36, v4, v5 offset1:1
	ds_write2_b32 v36, v6, v7 offset0:2 offset1:3
	ds_write2_b32 v38, v8, v9 offset1:1
	ds_write2_b32 v38, v10, v11 offset0:2 offset1:3
	ds_write2_b32 v40, v12, v13 offset1:1
	ds_write2_b32 v40, v14, v15 offset0:2 offset1:3
	ds_write2_b32 v42, v16, v17 offset1:1
	ds_write2_b32 v42, v18, v19 offset0:2 offset1:3
	v_mad_u64_u32 v[0:1], s[4:5], v69, s97, v[32:33]
	ds_write2_b32 v0, v20, v21 offset1:1
	ds_write2_b32 v0, v22, v23 offset0:2 offset1:3
	v_mad_u64_u32 v[0:1], s[4:5], v79, s97, v[32:33]
	ds_write2_b32 v0, v24, v25 offset1:1
	ds_write2_b32 v0, v26, v27 offset0:2 offset1:3
	v_mad_u64_u32 v[0:1], s[4:5], v80, s97, v[32:33]
	v_ashrrev_i32_e32 v2, 3, v33
	ds_write2_b32 v0, v28, v29 offset1:1
	ds_write2_b32 v0, v30, v31 offset0:2 offset1:3
	v_add_u32_e32 v0, s29, v2
	v_lshlrev_b32_e32 v3, 3, v33
	v_ashrrev_i32_e32 v1, 31, v0
	v_and_b32_e32 v3, 56, v3
	v_lshlrev_b32_e32 v2, 2, v2
	v_mul_u32_u24_e32 v4, 0x104, v3
	v_lshlrev_b64 v[0:1], 12, v[0:1]
	v_add3_u32 v32, 0, v2, v4
	v_lshl_add_u64 v[0:1], s[2:3], 0, v[0:1]
	v_lshl_add_u64 v[0:1], s[64:65], 1, v[0:1]
	v_lshlrev_b32_e32 v192, 1, v3
	v_add_u32_e32 v8, 0x400, v32
	s_waitcnt lgkmcnt(0)
	s_barrier
	v_lshl_add_u64 v[4:5], v[0:1], 0, v[192:193]
	ds_read2_b32 v[0:1], v32 offset1:65
	ds_read2_b32 v[2:3], v32 offset0:130 offset1:195
	ds_read2_b32 v[6:7], v8 offset0:4 offset1:69
	ds_read2_b32 v[8:9], v8 offset0:134 offset1:199
	v_add_u32_e32 v10, 0x4000, v32
	v_add_u32_e32 v12, 0x4200, v32
	v_add_u32_e32 v14, 0x4400, v32
	v_add_u32_e32 v16, 0x4600, v32
	v_add_u32_e32 v18, 0x8000, v32
	v_add_u32_e32 v22, 0x8400, v32
	ds_read2_b32 v[10:11], v10 offset0:64 offset1:129
	ds_read2_b32 v[12:13], v12 offset0:66 offset1:131
	ds_read2_b32 v[14:15], v14 offset0:68 offset1:133
	ds_read2_b32 v[16:17], v16 offset0:70 offset1:135
	ds_read2_b32 v[18:19], v18 offset0:128 offset1:193
	ds_read2_b32 v[20:21], v22 offset0:2 offset1:67
	ds_read2_b32 v[22:23], v22 offset0:132 offset1:197
	v_add_u32_e32 v24, 0x8800, v32
	v_add_u32_e32 v26, 0xc200, v32
	v_add_u32_e32 v28, 0xc400, v32
	v_add_u32_e32 v30, 0xc600, v32
	v_add_u32_e32 v32, 0xc800, v32
	ds_read2_b32 v[24:25], v24 offset0:6 offset1:71
	ds_read2_b32 v[26:27], v26 offset0:64 offset1:129
	ds_read2_b32 v[28:29], v28 offset0:66 offset1:131
	ds_read2_b32 v[30:31], v30 offset0:68 offset1:133
	ds_read2_b32 v[32:33], v32 offset0:70 offset1:135
	s_waitcnt lgkmcnt(14)
	v_cvt_pk_bf16_f32 v0, v0, v1
	v_cvt_pk_bf16_f32 v1, v2, v3
	s_waitcnt lgkmcnt(13)
	v_cvt_pk_bf16_f32 v2, v6, v7
	s_waitcnt lgkmcnt(12)
	v_cvt_pk_bf16_f32 v3, v8, v9
	global_store_dwordx4 v[4:5], v[0:3], off nt
	s_waitcnt lgkmcnt(11)
	s_nop 0
	v_cvt_pk_bf16_f32 v0, v10, v11
	s_waitcnt lgkmcnt(10)
	v_cvt_pk_bf16_f32 v1, v12, v13
	s_waitcnt lgkmcnt(9)
	v_cvt_pk_bf16_f32 v2, v14, v15
	s_waitcnt lgkmcnt(8)
	v_cvt_pk_bf16_f32 v3, v16, v17
	global_store_dwordx4 v[4:5], v[0:3], off offset:128 nt
	s_waitcnt lgkmcnt(7)
	s_nop 0
	v_cvt_pk_bf16_f32 v0, v18, v19
	s_waitcnt lgkmcnt(6)
	v_cvt_pk_bf16_f32 v1, v20, v21
	s_waitcnt lgkmcnt(5)
	v_cvt_pk_bf16_f32 v2, v22, v23
	s_waitcnt lgkmcnt(4)
	v_cvt_pk_bf16_f32 v3, v24, v25
	global_store_dwordx4 v[4:5], v[0:3], off offset:256 nt
	s_waitcnt lgkmcnt(3)
	s_nop 0
	v_cvt_pk_bf16_f32 v0, v26, v27
	s_waitcnt lgkmcnt(2)
	v_cvt_pk_bf16_f32 v1, v28, v29
	s_waitcnt lgkmcnt(1)
	v_cvt_pk_bf16_f32 v2, v30, v31
	s_waitcnt lgkmcnt(0)
	v_cvt_pk_bf16_f32 v3, v32, v33
	global_store_dwordx4 v[4:5], v[0:3], off offset:384 nt
	s_barrier

.LBB0_622:
	s_andn2_b64 vcc, exec, s[2:3]
	s_cbranch_vccnz .LBB0_628
	s_lshl_b32 s2, s28, 3
	s_and_b32 s29, s2, 0x1f00
	s_add_i32 s64, s29, 0xfffff000
	s_and_b32 s4, s28, 0x3c0
	s_and_b64 s[2:3], s[14:15], exec
	v_readlane_b32 s76, v253, 40
	s_cselect_b32 s2, 0x1000000, 0
	v_readlane_b32 s82, v253, 46
	v_readlane_b32 s83, v253, 47
	s_add_u32 s2, s82, s2
	s_addc_u32 s3, s83, 0
	s_lshl_b32 s5, s28, 6
	s_and_b32 s34, s5, 0x7c0
	s_lshl_b32 s5, s34, 2
	s_add_u32 s2, s2, s5
	s_addc_u32 s3, s3, 0
	s_cmpk_lg_i32 s4, 0x240
	s_mov_b64 s[4:5], -1
	v_readlane_b32 s77, v253, 41
	v_readlane_b32 s78, v253, 42
	v_readlane_b32 s79, v253, 43
	v_readlane_b32 s80, v253, 44
	v_readlane_b32 s81, v253, 45
	v_readlane_b32 s84, v253, 48
	v_readlane_b32 s85, v253, 49
	v_readlane_b32 s86, v253, 50
	v_readlane_b32 s87, v253, 51
	v_readlane_b32 s88, v253, 52
	v_readlane_b32 s89, v253, 53
	v_readlane_b32 s90, v253, 54
	v_readlane_b32 s91, v253, 55
	s_cbranch_scc0 .LBB0_625
	v_mov_b32_e32 v33, v224
	s_and_b64 s[4:5], s[14:15], exec
	v_add_u32_e32 v2, 0x200, v33
	v_add_u32_e32 v8, 0x400, v33
	v_add_u32_e32 v10, 0x600, v33
	v_add_u32_e32 v16, 0x800, v33
	v_add_u32_e32 v18, 0xa00, v33
	v_lshlrev_b32_e32 v0, 4, v33
	v_ashrrev_i32_e32 v34, 4, v33
	v_ashrrev_i32_e32 v36, 4, v2
	v_ashrrev_i32_e32 v38, 4, v8
	v_ashrrev_i32_e32 v40, 4, v10
	v_ashrrev_i32_e32 v42, 4, v16
	v_ashrrev_i32_e32 v69, 4, v18
	v_add_u32_e32 v24, 0xc00, v33
	v_and_b32_e32 v192, 0xf0, v0
	v_add_u32_e32 v0, s64, v34
	v_add_u32_e32 v2, s64, v36
	v_add_u32_e32 v8, s64, v38
	v_add_u32_e32 v10, s64, v40
	v_add_u32_e32 v16, s64, v42
	v_add_u32_e32 v18, s64, v69
	v_ashrrev_i32_e32 v79, 4, v24
	v_add_u32_e32 v30, 0xe00, v33
	s_waitcnt lgkmcnt(0)
	v_ashrrev_i32_e32 v1, 31, v0
	v_ashrrev_i32_e32 v3, 31, v2
	v_ashrrev_i32_e32 v9, 31, v8
	v_ashrrev_i32_e32 v11, 31, v10
	v_ashrrev_i32_e32 v17, 31, v16
	v_ashrrev_i32_e32 v19, 31, v18
	v_add_u32_e32 v24, s64, v79
	v_ashrrev_i32_e32 v96, 4, v30
	v_lshl_add_u64 v[28:29], s[2:3], 0, v[192:193]
	v_lshlrev_b64 v[0:1], 13, v[0:1]
	v_lshlrev_b64 v[2:3], 13, v[2:3]
	v_lshlrev_b64 v[8:9], 13, v[8:9]
	v_lshlrev_b64 v[10:11], 13, v[10:11]
	v_lshlrev_b64 v[16:17], 13, v[16:17]
	v_lshlrev_b64 v[18:19], 13, v[18:19]
	v_ashrrev_i32_e32 v25, 31, v24
	v_add_u32_e32 v30, s64, v96
	v_lshl_add_u64 v[0:1], v[28:29], 0, v[0:1]
	v_lshl_add_u64 v[4:5], v[28:29], 0, v[2:3]
	v_lshl_add_u64 v[8:9], v[28:29], 0, v[8:9]
	v_lshl_add_u64 v[12:13], v[28:29], 0, v[10:11]
	v_lshl_add_u64 v[16:17], v[28:29], 0, v[16:17]
	v_lshl_add_u64 v[20:21], v[28:29], 0, v[18:19]
	v_lshlrev_b64 v[24:25], 13, v[24:25]
	v_ashrrev_i32_e32 v31, 31, v30
	global_load_dwordx4 v[0:3], v[0:1], off nt
	s_nop 0
	global_load_dwordx4 v[4:7], v[4:5], off nt
	s_nop 0
	global_load_dwordx4 v[8:11], v[8:9], off nt
	s_nop 0
	global_load_dwordx4 v[12:15], v[12:13], off nt
	s_nop 0
	global_load_dwordx4 v[16:19], v[16:17], off nt
	s_nop 0
	global_load_dwordx4 v[20:23], v[20:21], off nt
	v_lshl_add_u64 v[24:25], v[28:29], 0, v[24:25]
	v_lshlrev_b64 v[30:31], 13, v[30:31]
	global_load_dwordx4 v[24:27], v[24:25], off nt
	v_lshl_add_u64 v[28:29], v[28:29], 0, v[30:31]
	global_load_dwordx4 v[28:31], v[28:29], off nt
	v_add_u32_e32 v32, 0, v192
	v_mad_u64_u32 v[34:35], s[46:47], v34, s97, v[32:33]
	v_mad_u64_u32 v[36:37], s[46:47], v36, s97, v[32:33]
	v_mad_u64_u32 v[38:39], s[46:47], v38, s97, v[32:33]
	v_mad_u64_u32 v[40:41], s[46:47], v40, s97, v[32:33]
	v_mad_u64_u32 v[42:43], s[46:47], v42, s97, v[32:33]
	v_mad_u64_u32 v[80:81], s[46:47], v69, s97, v[32:33]
	s_cselect_b32 s4, 0x800000, 0
	v_readlane_b32 s5, v252, 3
	s_add_u32 s4, s5, s4
	v_readlane_b32 s5, v252, 4
	s_addc_u32 s5, s5, 0
	s_mov_b32 s9, 0xc000
	s_waitcnt vmcnt(0)
	ds_write2_b32 v34, v0, v1 offset1:1
	ds_write2_b32 v34, v2, v3 offset0:2 offset1:3
	ds_write2_b32 v36, v4, v5 offset1:1
	ds_write2_b32 v36, v6, v7 offset0:2 offset1:3
	ds_write2_b32 v38, v8, v9 offset1:1
	ds_write2_b32 v38, v10, v11 offset0:2 offset1:3
	ds_write2_b32 v40, v12, v13 offset1:1
	ds_write2_b32 v40, v14, v15 offset0:2 offset1:3
	ds_write2_b32 v42, v16, v17 offset1:1
	ds_write2_b32 v42, v18, v19 offset0:2 offset1:3
	ds_write2_b32 v80, v20, v21 offset1:1
	ds_write2_b32 v80, v22, v23 offset0:2 offset1:3
	v_mad_u64_u32 v[0:1], s[46:47], v79, s97, v[32:33]
	ds_write2_b32 v0, v24, v25 offset1:1
	ds_write2_b32 v0, v26, v27 offset0:2 offset1:3
	v_mad_u64_u32 v[0:1], s[46:47], v96, s97, v[32:33]
	v_ashrrev_i32_e32 v2, 3, v33
	ds_write2_b32 v0, v28, v29 offset1:1
	ds_write2_b32 v0, v30, v31 offset0:2 offset1:3
	v_add_u32_e32 v0, s34, v2
	v_lshlrev_b32_e32 v3, 3, v33
	v_ashrrev_i32_e32 v1, 31, v0
	v_and_b32_e32 v3, 56, v3
	v_lshlrev_b32_e32 v2, 2, v2
	v_mul_u32_u24_e32 v4, 0x104, v3
	v_lshlrev_b64 v[0:1], 12, v[0:1]
	v_add3_u32 v32, 0, v2, v4
	v_lshl_add_u64 v[0:1], s[4:5], 0, v[0:1]
	v_lshl_add_u64 v[0:1], s[64:65], 1, v[0:1]
	v_lshlrev_b32_e32 v192, 1, v3
	v_add_u32_e32 v8, 0x400, v32
	s_waitcnt lgkmcnt(0)
	s_barrier
	v_lshl_add_u64 v[4:5], v[0:1], 0, v[192:193]
	ds_read2_b32 v[0:1], v32 offset1:65
	ds_read2_b32 v[2:3], v32 offset0:130 offset1:195
	ds_read2_b32 v[6:7], v8 offset0:4 offset1:69
	ds_read2_b32 v[8:9], v8 offset0:134 offset1:199
	v_add_u32_e32 v10, 0x4000, v32
	v_add_u32_e32 v12, 0x4200, v32
	v_add_u32_e32 v14, 0x4400, v32
	v_add_u32_e32 v16, 0x4600, v32
	v_add_u32_e32 v18, 0x8000, v32
	v_add_u32_e32 v22, 0x8400, v32
	ds_read2_b32 v[10:11], v10 offset0:64 offset1:129
	ds_read2_b32 v[12:13], v12 offset0:66 offset1:131
	ds_read2_b32 v[14:15], v14 offset0:68 offset1:133
	ds_read2_b32 v[16:17], v16 offset0:70 offset1:135
	ds_read2_b32 v[18:19], v18 offset0:128 offset1:193
	ds_read2_b32 v[20:21], v22 offset0:2 offset1:67
	ds_read2_b32 v[22:23], v22 offset0:132 offset1:197
	v_add_u32_e32 v24, 0x8800, v32
	v_add_u32_e32 v26, 0xc200, v32
	v_add_u32_e32 v28, 0xc400, v32
	v_add_u32_e32 v30, 0xc600, v32
	v_add_u32_e32 v32, 0xc800, v32
	ds_read2_b32 v[24:25], v24 offset0:6 offset1:71
	ds_read2_b32 v[26:27], v26 offset0:64 offset1:129
	ds_read2_b32 v[28:29], v28 offset0:66 offset1:131
	ds_read2_b32 v[30:31], v30 offset0:68 offset1:133
	ds_read2_b32 v[32:33], v32 offset0:70 offset1:135
	s_waitcnt lgkmcnt(14)
	v_cvt_pk_bf16_f32 v0, v0, v1
	v_cvt_pk_bf16_f32 v1, v2, v3
	s_waitcnt lgkmcnt(13)
	v_cvt_pk_bf16_f32 v2, v6, v7
	s_waitcnt lgkmcnt(12)
	v_cvt_pk_bf16_f32 v3, v8, v9
	global_store_dwordx4 v[4:5], v[0:3], off nt
	s_mov_b64 s[4:5], 0
	s_waitcnt lgkmcnt(11)
	v_cvt_pk_bf16_f32 v0, v10, v11
	s_waitcnt lgkmcnt(10)
	v_cvt_pk_bf16_f32 v1, v12, v13
	s_waitcnt lgkmcnt(9)
	v_cvt_pk_bf16_f32 v2, v14, v15
	s_waitcnt lgkmcnt(8)
	v_cvt_pk_bf16_f32 v3, v16, v17
	global_store_dwordx4 v[4:5], v[0:3], off offset:128 nt
	s_waitcnt lgkmcnt(7)
	s_nop 0
	v_cvt_pk_bf16_f32 v0, v18, v19
	s_waitcnt lgkmcnt(6)
	v_cvt_pk_bf16_f32 v1, v20, v21
	s_waitcnt lgkmcnt(5)
	v_cvt_pk_bf16_f32 v2, v22, v23
	s_waitcnt lgkmcnt(4)
	v_cvt_pk_bf16_f32 v3, v24, v25
	global_store_dwordx4 v[4:5], v[0:3], off offset:256 nt
	s_waitcnt lgkmcnt(3)
	s_nop 0
	v_cvt_pk_bf16_f32 v0, v26, v27
	s_waitcnt lgkmcnt(2)
	v_cvt_pk_bf16_f32 v1, v28, v29
	s_waitcnt lgkmcnt(1)
	v_cvt_pk_bf16_f32 v2, v30, v31
	s_waitcnt lgkmcnt(0)
	v_cvt_pk_bf16_f32 v3, v32, v33
	global_store_dwordx4 v[4:5], v[0:3], off offset:384 nt
	s_barrier
.LBB0_625:
	s_andn2_b64 vcc, exec, s[4:5]
	s_cbranch_vccnz .LBB0_627
	v_mov_b32_e32 v33, v224
	s_nop 0
	v_add_u32_e32 v2, 0x200, v33
	v_add_u32_e32 v8, 0x400, v33
	v_add_u32_e32 v10, 0x600, v33
	v_add_u32_e32 v16, 0x800, v33
	v_add_u32_e32 v18, 0xa00, v33
	v_lshlrev_b32_e32 v0, 4, v33
	v_ashrrev_i32_e32 v34, 4, v33
	v_ashrrev_i32_e32 v36, 4, v2
	v_ashrrev_i32_e32 v38, 4, v8
	v_ashrrev_i32_e32 v40, 4, v10
	v_ashrrev_i32_e32 v42, 4, v16
	v_ashrrev_i32_e32 v69, 4, v18
	v_add_u32_e32 v24, 0xc00, v33
	v_and_b32_e32 v192, 0xf0, v0
	v_add_u32_e32 v0, s64, v34
	v_add_u32_e32 v2, s64, v36
	v_add_u32_e32 v8, s64, v38
	v_add_u32_e32 v10, s64, v40
	v_add_u32_e32 v16, s64, v42
	v_add_u32_e32 v18, s64, v69
	v_ashrrev_i32_e32 v79, 4, v24
	v_add_u32_e32 v30, 0xe00, v33
	s_waitcnt lgkmcnt(0)
	v_ashrrev_i32_e32 v1, 31, v0
	v_ashrrev_i32_e32 v3, 31, v2
	v_ashrrev_i32_e32 v9, 31, v8
	v_ashrrev_i32_e32 v11, 31, v10
	v_ashrrev_i32_e32 v17, 31, v16
	v_ashrrev_i32_e32 v19, 31, v18
	v_add_u32_e32 v24, s64, v79
	v_ashrrev_i32_e32 v96, 4, v30
	v_lshl_add_u64 v[28:29], s[2:3], 0, v[192:193]
	v_lshlrev_b64 v[0:1], 13, v[0:1]
	v_lshlrev_b64 v[2:3], 13, v[2:3]
	v_lshlrev_b64 v[8:9], 13, v[8:9]
	v_lshlrev_b64 v[10:11], 13, v[10:11]
	v_lshlrev_b64 v[16:17], 13, v[16:17]
	v_lshlrev_b64 v[18:19], 13, v[18:19]
	v_ashrrev_i32_e32 v25, 31, v24
	v_add_u32_e32 v30, s64, v96
	v_lshl_add_u64 v[0:1], v[28:29], 0, v[0:1]
	v_lshl_add_u64 v[4:5], v[28:29], 0, v[2:3]
	v_lshl_add_u64 v[8:9], v[28:29], 0, v[8:9]
	v_lshl_add_u64 v[12:13], v[28:29], 0, v[10:11]
	v_lshl_add_u64 v[16:17], v[28:29], 0, v[16:17]
	v_lshl_add_u64 v[20:21], v[28:29], 0, v[18:19]
	v_lshlrev_b64 v[24:25], 13, v[24:25]
	v_ashrrev_i32_e32 v31, 31, v30
	global_load_dwordx4 v[0:3], v[0:1], off nt
	s_nop 0
	global_load_dwordx4 v[4:7], v[4:5], off nt
	s_nop 0
	global_load_dwordx4 v[8:11], v[8:9], off nt
	s_nop 0
	global_load_dwordx4 v[12:15], v[12:13], off nt
	s_nop 0
	global_load_dwordx4 v[16:19], v[16:17], off nt
	s_nop 0
	global_load_dwordx4 v[20:23], v[20:21], off nt
	v_lshl_add_u64 v[24:25], v[28:29], 0, v[24:25]
	v_lshlrev_b64 v[30:31], 13, v[30:31]
	global_load_dwordx4 v[24:27], v[24:25], off nt
	v_lshl_add_u64 v[28:29], v[28:29], 0, v[30:31]
	global_load_dwordx4 v[28:31], v[28:29], off nt
	v_add_u32_e32 v32, 0, v192
	v_mad_u64_u32 v[34:35], s[4:5], v34, s97, v[32:33]
	v_mad_u64_u32 v[36:37], s[4:5], v36, s97, v[32:33]
	v_mad_u64_u32 v[38:39], s[4:5], v38, s97, v[32:33]
	v_mad_u64_u32 v[40:41], s[4:5], v40, s97, v[32:33]
	v_mad_u64_u32 v[42:43], s[4:5], v42, s97, v[32:33]
	v_mad_u64_u32 v[80:81], s[4:5], v69, s97, v[32:33]
	s_and_b64 s[2:3], s[14:15], exec
	s_cselect_b32 s2, 0x200000, 0
	s_add_u32 s2, s26, s2
	s_addc_u32 s3, s27, 0
	s_lshl_b32 s64, s29, 1
	s_waitcnt vmcnt(0)
	ds_write2_b32 v34, v0, v1 offset1:1
	ds_write2_b32 v34, v2, v3 offset0:2 offset1:3
	ds_write2_b32 v36, v4, v5 offset1:1
	ds_write2_b32 v36, v6, v7 offset0:2 offset1:3
	ds_write2_b32 v38, v8, v9 offset1:1
	ds_write2_b32 v38, v10, v11 offset0:2 offset1:3
	ds_write2_b32 v40, v12, v13 offset1:1
	ds_write2_b32 v40, v14, v15 offset0:2 offset1:3
	ds_write2_b32 v42, v16, v17 offset1:1
	ds_write2_b32 v42, v18, v19 offset0:2 offset1:3
	ds_write2_b32 v80, v20, v21 offset1:1
	ds_write2_b32 v80, v22, v23 offset0:2 offset1:3
	v_mad_u64_u32 v[0:1], s[4:5], v79, s97, v[32:33]
	ds_write2_b32 v0, v24, v25 offset1:1
	ds_write2_b32 v0, v26, v27 offset0:2 offset1:3
	v_mad_u64_u32 v[0:1], s[4:5], v96, s97, v[32:33]
	v_ashrrev_i32_e32 v2, 3, v33
	ds_write2_b32 v0, v28, v29 offset1:1
	ds_write2_b32 v0, v30, v31 offset0:2 offset1:3
	v_add_u32_e32 v0, s34, v2
	v_lshlrev_b32_e32 v3, 3, v33
	v_ashrrev_i32_e32 v1, 31, v0
	v_and_b32_e32 v3, 56, v3
	v_lshlrev_b32_e32 v2, 2, v2
	v_mul_u32_u24_e32 v4, 0x104, v3
	v_lshlrev_b64 v[0:1], 10, v[0:1]
	v_add3_u32 v34, 0, v2, v4
	v_lshl_add_u64 v[0:1], s[2:3], 0, v[0:1]
	v_lshl_add_u64 v[0:1], v[0:1], 0, s[64:65]
	v_lshlrev_b32_e32 v192, 1, v3
	v_add_u32_e32 v10, 0x400, v34
	s_waitcnt lgkmcnt(0)
	s_barrier
	v_lshl_add_u64 v[4:5], v[0:1], 0, v[192:193]
	ds_read2_b32 v[0:1], v34 offset1:65
	ds_read2_b32 v[2:3], v34 offset0:130 offset1:195
	ds_read2_b32 v[8:9], v10 offset0:4 offset1:69
	ds_read2_b32 v[10:11], v10 offset0:134 offset1:199
	v_add_u32_e32 v12, 0x4000, v34
	v_add_u32_e32 v14, 0x4200, v34
	v_add_u32_e32 v16, 0x4400, v34
	v_add_u32_e32 v18, 0x4600, v34
	v_add_u32_e32 v20, 0x8000, v34
	v_add_u32_e32 v24, 0x8400, v34
	s_mov_b64 s[2:3], 0x3dfdc00
	ds_read2_b32 v[12:13], v12 offset0:64 offset1:129
	ds_read2_b32 v[14:15], v14 offset0:66 offset1:131
	ds_read2_b32 v[16:17], v16 offset0:68 offset1:133
	ds_read2_b32 v[18:19], v18 offset0:70 offset1:135
	ds_read2_b32 v[20:21], v20 offset0:128 offset1:193
	ds_read2_b32 v[22:23], v24 offset0:2 offset1:67
	ds_read2_b32 v[24:25], v24 offset0:132 offset1:197
	v_lshl_add_u64 v[6:7], v[4:5], 0, s[2:3]
	s_mov_b32 s2, 0x3dfd000
	v_add_u32_e32 v26, 0x8800, v34
	v_add_u32_e32 v28, 0xc200, v34
	v_add_u32_e32 v30, 0xc400, v34
	v_add_u32_e32 v32, 0xc600, v34
	v_add_u32_e32 v34, 0xc800, v34
	v_add_co_u32_e32 v4, vcc, s2, v4
	ds_read2_b32 v[26:27], v26 offset0:6 offset1:71
	ds_read2_b32 v[28:29], v28 offset0:64 offset1:129
	ds_read2_b32 v[30:31], v30 offset0:66 offset1:131
	ds_read2_b32 v[32:33], v32 offset0:68 offset1:133
	ds_read2_b32 v[34:35], v34 offset0:70 offset1:135
	s_waitcnt lgkmcnt(14)
	v_cvt_pk_bf16_f32 v0, v0, v1
	v_cvt_pk_bf16_f32 v1, v2, v3
	s_waitcnt lgkmcnt(13)
	v_cvt_pk_bf16_f32 v2, v8, v9
	s_waitcnt lgkmcnt(12)
	v_cvt_pk_bf16_f32 v3, v10, v11
	v_addc_co_u32_e32 v5, vcc, 0, v5, vcc
	global_store_dwordx4 v[4:5], v[0:3], off offset:3072 nt
	s_waitcnt lgkmcnt(11)
	s_nop 0
	v_cvt_pk_bf16_f32 v0, v12, v13
	s_waitcnt lgkmcnt(10)
	v_cvt_pk_bf16_f32 v1, v14, v15
	s_waitcnt lgkmcnt(9)
	v_cvt_pk_bf16_f32 v2, v16, v17
	s_waitcnt lgkmcnt(8)
	v_cvt_pk_bf16_f32 v3, v18, v19
	global_store_dwordx4 v[6:7], v[0:3], off offset:128 nt
	s_waitcnt lgkmcnt(7)
	s_nop 0
	v_cvt_pk_bf16_f32 v0, v20, v21
	s_waitcnt lgkmcnt(6)
	v_cvt_pk_bf16_f32 v1, v22, v23
	s_waitcnt lgkmcnt(5)
	v_cvt_pk_bf16_f32 v2, v24, v25
	s_waitcnt lgkmcnt(4)
	v_cvt_pk_bf16_f32 v3, v26, v27
	global_store_dwordx4 v[6:7], v[0:3], off offset:256 nt
	s_waitcnt lgkmcnt(3)
	s_nop 0
	v_cvt_pk_bf16_f32 v0, v28, v29
	s_waitcnt lgkmcnt(2)
	v_cvt_pk_bf16_f32 v1, v30, v31
	s_waitcnt lgkmcnt(1)
	v_cvt_pk_bf16_f32 v2, v32, v33
	s_waitcnt lgkmcnt(0)
	v_cvt_pk_bf16_f32 v3, v34, v35
	global_store_dwordx4 v[6:7], v[0:3], off offset:384 nt
	s_barrier

.LBB0_636:
	s_andn2_saveexec_b64 s[2:3], s[2:3]
	v_add_u32_e32 v4, s28, v3
	v_lshrrev_b32_e32 v0, 3, v2
	v_lshlrev_b32_e32 v1, 1, v1
	v_ashrrev_i32_e32 v4, 7, v4
	v_and_b32_e32 v1, 0x3f8, v1
	v_bfi_b32 v0, -4, v4, v0
	s_movk_i32 s4, 0x800
	v_add3_u32 v0, v0, v1, s4
	s_or_b64 exec, exec, s[2:3]
	s_and_b64 s[2:3], s[14:15], exec
	s_cselect_b32 s2, 0x1400000, 0
	v_lshlrev_b32_e32 v2, 3, v2
	s_add_u32 s2, s26, s2
	v_ashrrev_i32_e32 v1, 31, v0
	v_and_b32_e32 v2, 56, v2
	s_addc_u32 s3, s27, 0
	v_lshlrev_b64 v[0:1], 12, v[0:1]
	v_lshlrev_b32_e32 v3, 2, v3
	v_mul_u32_u24_e32 v4, 0x104, v2
	v_add3_u32 v32, 0, v3, v4
	v_lshl_add_u64 v[0:1], s[2:3], 0, v[0:1]
	s_lshl_b32 s64, s29, 1
	v_lshl_add_u64 v[0:1], v[0:1], 0, s[64:65]
	v_lshlrev_b32_e32 v192, 1, v2
	v_add_u32_e32 v8, 0x400, v32
	v_lshl_add_u64 v[4:5], v[0:1], 0, v[192:193]
	ds_read2_b32 v[0:1], v32 offset1:65
	ds_read2_b32 v[2:3], v32 offset0:130 offset1:195
	ds_read2_b32 v[6:7], v8 offset0:4 offset1:69
	ds_read2_b32 v[8:9], v8 offset0:134 offset1:199
	v_add_u32_e32 v10, 0x4000, v32
	v_add_u32_e32 v12, 0x4200, v32
	v_add_u32_e32 v14, 0x4400, v32
	v_add_u32_e32 v16, 0x4600, v32
	v_add_u32_e32 v18, 0x8000, v32
	v_add_u32_e32 v22, 0x8400, v32
	ds_read2_b32 v[10:11], v10 offset0:64 offset1:129
	ds_read2_b32 v[12:13], v12 offset0:66 offset1:131
	ds_read2_b32 v[14:15], v14 offset0:68 offset1:133
	ds_read2_b32 v[16:17], v16 offset0:70 offset1:135
	ds_read2_b32 v[18:19], v18 offset0:128 offset1:193
	ds_read2_b32 v[20:21], v22 offset0:2 offset1:67
	ds_read2_b32 v[22:23], v22 offset0:132 offset1:197
	v_add_u32_e32 v24, 0x8800, v32
	v_add_u32_e32 v26, 0xc200, v32
	v_add_u32_e32 v28, 0xc400, v32
	v_add_u32_e32 v30, 0xc600, v32
	v_add_u32_e32 v32, 0xc800, v32
	ds_read2_b32 v[24:25], v24 offset0:6 offset1:71
	ds_read2_b32 v[26:27], v26 offset0:64 offset1:129
	ds_read2_b32 v[28:29], v28 offset0:66 offset1:131
	ds_read2_b32 v[30:31], v30 offset0:68 offset1:133
	ds_read2_b32 v[32:33], v32 offset0:70 offset1:135
	s_waitcnt lgkmcnt(14)
	v_cvt_pk_bf16_f32 v0, v0, v1
	v_cvt_pk_bf16_f32 v1, v2, v3
	s_waitcnt lgkmcnt(13)
	v_cvt_pk_bf16_f32 v2, v6, v7
	s_waitcnt lgkmcnt(12)
	v_cvt_pk_bf16_f32 v3, v8, v9
	global_store_dwordx4 v[4:5], v[0:3], off nt
	v_readlane_b32 s76, v254, 63
	v_readlane_b32 s77, v255, 0
	s_waitcnt lgkmcnt(11)
	v_cvt_pk_bf16_f32 v0, v10, v11
	s_waitcnt lgkmcnt(10)
	v_cvt_pk_bf16_f32 v1, v12, v13
	s_waitcnt lgkmcnt(9)
	v_cvt_pk_bf16_f32 v2, v14, v15
	s_waitcnt lgkmcnt(8)
	v_cvt_pk_bf16_f32 v3, v16, v17
	global_store_dwordx4 v[4:5], v[0:3], off offset:128 nt
	s_movk_i32 s30, 0x1000
	s_mov_b64 s[78:79], 0x2000
	s_waitcnt lgkmcnt(7)
	v_cvt_pk_bf16_f32 v0, v18, v19
	s_waitcnt lgkmcnt(6)
	v_cvt_pk_bf16_f32 v1, v20, v21
	s_waitcnt lgkmcnt(5)
	v_cvt_pk_bf16_f32 v2, v22, v23
	s_waitcnt lgkmcnt(4)
	v_cvt_pk_bf16_f32 v3, v24, v25
	global_store_dwordx4 v[4:5], v[0:3], off offset:256 nt
	s_waitcnt lgkmcnt(3)
	s_nop 0
	v_cvt_pk_bf16_f32 v0, v26, v27
	s_waitcnt lgkmcnt(2)
	v_cvt_pk_bf16_f32 v1, v28, v29
	s_waitcnt lgkmcnt(1)
	v_cvt_pk_bf16_f32 v2, v30, v31
	s_waitcnt lgkmcnt(0)
	v_cvt_pk_bf16_f32 v3, v32, v33
	global_store_dwordx4 v[4:5], v[0:3], off offset:384 nt
	s_barrier
